# v34: v29 + epilogue operands (rinv rows; first-row cos/sin in layer B) requested from inside the last k-iteration, all hand-written epilogue paths consume them
# speedup vs baseline: 1.0125x; 1.0038x over previous
.LBB0_452:
	s_mov_b32 s0, 0xbb7be14b
	s_mov_b32 s2, 0x3bcff2a2
	s_mov_b32 s28, 0xbc40d0ac
	s_mov_b32 s30, 0x3cb76c34
	s_mov_b32 s48, 0xbd17b858
	s_mov_b32 s50, 0x3d6537d1
	s_mov_b32 s52, 0xbdacab04
	s_mov_b32 s54, 0x3e342bfa
	v_mov_b32_e32 v198, s0
	v_and_b32_e32 v147, 64, v223
	v_add_u32_e32 v147, 64, v147
	v_xor_b32_e32 v146, 16, v223
	v_cmp_lt_i32_e32 vcc, v146, v147
	s_nop 1
	v_cndmask_b32_e32 v146, v223, v146, vcc
	v_lshlrev_b32_e32 v146, 2, v146
	v_xor_b32_e32 v148, 32, v223
	v_cmp_lt_i32_e32 vcc, v148, v147
	s_nop 1
	v_cndmask_b32_e32 v147, v223, v148, vcc
	v_lshlrev_b32_e32 v147, 2, v147
	s_add_i32 s94, s47, -16
	v_lshl_or_b32 v145, s94, 8, v176
	v_lshlrev_b32_e32 v148, 12, v142
	v_lshl_add_u32 v201, v145, 1, v148
	s_lshl_b32 s94, s94, 2
	s_or_b32 s94, s94, s43
	s_lshl_b32 s94, s94, 3
	v_lshlrev_b32_e32 v148, 8, v142
	v_add_u32_e32 v216, s94, v148
	v_add_u32_e32 v203, 0x10000, v201
	v_add_u32_e32 v217, 0x1000, v216
	v_add_u32_e32 v205, 0x20000, v201
	v_add_u32_e32 v218, 0x2000, v216
	v_add_u32_e32 v207, 0x30000, v201
	v_add_u32_e32 v219, 0x3000, v216
	v_add_u32_e32 v209, 0x80000, v201
	v_add_u32_e32 v220, 0x8000, v216
	v_add_u32_e32 v211, 0x90000, v201
	v_add_u32_e32 v221, 0x9000, v216
	v_add_u32_e32 v213, 0xa0000, v201
	v_add_u32_e32 v186, 0xa000, v216
	v_add_u32_e32 v215, 0xb0000, v201
	v_add_u32_e32 v187, 0xb000, v216
	s_waitcnt vmcnt(0)
	v_pk_mul_f32 v[128:129], v[128:129], v[236:237] op_sel_hi:[1,0]
	v_pk_mul_f32 v[130:131], v[130:131], v[236:237] op_sel_hi:[1,0]
	v_pk_mul_f32 v[120:121], v[120:121], v[236:237] op_sel_hi:[1,0]
	v_pk_mul_f32 v[122:123], v[122:123], v[236:237] op_sel_hi:[1,0]
	v_pk_mul_f32 v[124:125], v[124:125], v[236:237] op_sel_hi:[1,0]
	v_pk_mul_f32 v[126:127], v[126:127], v[236:237] op_sel_hi:[1,0]
	v_pk_mul_f32 v[116:117], v[116:117], v[236:237] op_sel_hi:[1,0]
	v_pk_mul_f32 v[118:119], v[118:119], v[236:237] op_sel_hi:[1,0]
	v_med3_f32 v158, v128, -4.0, 4.0
	v_med3_f32 v164, v130, -4.0, 4.0
	v_med3_f32 v170, v120, -4.0, 4.0
	v_med3_f32 v180, v122, -4.0, 4.0
	v_med3_f32 v159, v129, -4.0, 4.0
	v_med3_f32 v165, v131, -4.0, 4.0
	v_med3_f32 v171, v121, -4.0, 4.0
	v_med3_f32 v181, v123, -4.0, 4.0
	v_pk_mul_f32 v[160:161], v[158:159], v[158:159]
	v_pk_mul_f32 v[166:167], v[164:165], v[164:165]
	v_pk_mul_f32 v[172:173], v[170:171], v[170:171]
	v_pk_mul_f32 v[182:183], v[180:181], v[180:181]
	v_pk_fma_f32 v[160:161], v[160:161], s[72:73], -1.0 op_sel_hi:[1,0,0]
	v_pk_fma_f32 v[166:167], v[166:167], s[72:73], -1.0 op_sel_hi:[1,0,0]
	v_pk_fma_f32 v[172:173], v[172:173], s[72:73], -1.0 op_sel_hi:[1,0,0]
	v_pk_fma_f32 v[182:183], v[182:183], s[72:73], -1.0 op_sel_hi:[1,0,0]
	v_pk_fma_f32 v[162:163], v[160:161], s[74:75], v[198:199] op_sel_hi:[1,0,0]
	v_pk_fma_f32 v[168:169], v[166:167], s[74:75], v[198:199] op_sel_hi:[1,0,0]
	v_pk_fma_f32 v[178:179], v[172:173], s[74:75], v[198:199] op_sel_hi:[1,0,0]
	v_pk_fma_f32 v[184:185], v[182:183], s[74:75], v[198:199] op_sel_hi:[1,0,0]
	v_pk_fma_f32 v[162:163], v[160:161], v[162:163], s[2:3] op_sel_hi:[1,1,0]
	v_pk_fma_f32 v[168:169], v[166:167], v[168:169], s[2:3] op_sel_hi:[1,1,0]
	v_pk_fma_f32 v[178:179], v[172:173], v[178:179], s[2:3] op_sel_hi:[1,1,0]
	v_pk_fma_f32 v[184:185], v[182:183], v[184:185], s[2:3] op_sel_hi:[1,1,0]
	v_pk_fma_f32 v[162:163], v[160:161], v[162:163], s[28:29] op_sel_hi:[1,1,0]
	v_pk_fma_f32 v[168:169], v[166:167], v[168:169], s[28:29] op_sel_hi:[1,1,0]
	v_pk_fma_f32 v[178:179], v[172:173], v[178:179], s[28:29] op_sel_hi:[1,1,0]
	v_pk_fma_f32 v[184:185], v[182:183], v[184:185], s[28:29] op_sel_hi:[1,1,0]
	v_pk_fma_f32 v[162:163], v[160:161], v[162:163], s[30:31] op_sel_hi:[1,1,0]
	v_pk_fma_f32 v[168:169], v[166:167], v[168:169], s[30:31] op_sel_hi:[1,1,0]
	v_pk_fma_f32 v[178:179], v[172:173], v[178:179], s[30:31] op_sel_hi:[1,1,0]
	v_pk_fma_f32 v[184:185], v[182:183], v[184:185], s[30:31] op_sel_hi:[1,1,0]
	v_pk_fma_f32 v[162:163], v[160:161], v[162:163], s[48:49] op_sel_hi:[1,1,0]
	v_pk_fma_f32 v[168:169], v[166:167], v[168:169], s[48:49] op_sel_hi:[1,1,0]
	v_pk_fma_f32 v[178:179], v[172:173], v[178:179], s[48:49] op_sel_hi:[1,1,0]
	v_pk_fma_f32 v[184:185], v[182:183], v[184:185], s[48:49] op_sel_hi:[1,1,0]
	v_pk_fma_f32 v[162:163], v[160:161], v[162:163], s[50:51] op_sel_hi:[1,1,0]
	v_pk_fma_f32 v[168:169], v[166:167], v[168:169], s[50:51] op_sel_hi:[1,1,0]
	v_pk_fma_f32 v[178:179], v[172:173], v[178:179], s[50:51] op_sel_hi:[1,1,0]
	v_pk_fma_f32 v[184:185], v[182:183], v[184:185], s[50:51] op_sel_hi:[1,1,0]
	v_pk_fma_f32 v[162:163], v[160:161], v[162:163], s[52:53] op_sel_hi:[1,1,0]
	v_pk_fma_f32 v[168:169], v[166:167], v[168:169], s[52:53] op_sel_hi:[1,1,0]
	v_pk_fma_f32 v[178:179], v[172:173], v[178:179], s[52:53] op_sel_hi:[1,1,0]
	v_pk_fma_f32 v[184:185], v[182:183], v[184:185], s[52:53] op_sel_hi:[1,1,0]
	v_pk_fma_f32 v[160:161], v[160:161], v[162:163], s[54:55] op_sel_hi:[1,1,0]
	v_pk_fma_f32 v[166:167], v[166:167], v[168:169], s[54:55] op_sel_hi:[1,1,0]
	v_pk_fma_f32 v[172:173], v[172:173], v[178:179], s[54:55] op_sel_hi:[1,1,0]
	v_pk_fma_f32 v[182:183], v[182:183], v[184:185], s[54:55] op_sel_hi:[1,1,0]
	v_pk_fma_f32 v[158:159], v[158:159], v[160:161], 0.5 op_sel_hi:[1,1,0]
	v_pk_fma_f32 v[164:165], v[164:165], v[166:167], 0.5 op_sel_hi:[1,1,0]
	v_pk_fma_f32 v[170:171], v[170:171], v[172:173], 0.5 op_sel_hi:[1,1,0]
	v_pk_fma_f32 v[180:181], v[180:181], v[182:183], 0.5 op_sel_hi:[1,1,0]
	v_pk_mul_f32 v[128:129], v[128:129], v[158:159]
	v_pk_mul_f32 v[130:131], v[130:131], v[164:165]
	v_pk_mul_f32 v[120:121], v[120:121], v[170:171]
	v_pk_mul_f32 v[122:123], v[122:123], v[180:181]
	v_med3_f32 v158, v124, -4.0, 4.0
	v_med3_f32 v164, v126, -4.0, 4.0
	v_med3_f32 v170, v116, -4.0, 4.0
	v_med3_f32 v180, v118, -4.0, 4.0
	v_med3_f32 v159, v125, -4.0, 4.0
	v_med3_f32 v165, v127, -4.0, 4.0
	v_med3_f32 v171, v117, -4.0, 4.0
	v_med3_f32 v181, v119, -4.0, 4.0
	v_pk_mul_f32 v[160:161], v[158:159], v[158:159]
	v_pk_mul_f32 v[166:167], v[164:165], v[164:165]
	v_pk_mul_f32 v[172:173], v[170:171], v[170:171]
	v_pk_mul_f32 v[182:183], v[180:181], v[180:181]
	v_pk_fma_f32 v[160:161], v[160:161], s[72:73], -1.0 op_sel_hi:[1,0,0]
	v_pk_fma_f32 v[166:167], v[166:167], s[72:73], -1.0 op_sel_hi:[1,0,0]
	v_pk_fma_f32 v[172:173], v[172:173], s[72:73], -1.0 op_sel_hi:[1,0,0]
	v_pk_fma_f32 v[182:183], v[182:183], s[72:73], -1.0 op_sel_hi:[1,0,0]
	v_pk_fma_f32 v[162:163], v[160:161], s[74:75], v[198:199] op_sel_hi:[1,0,0]
	v_pk_fma_f32 v[168:169], v[166:167], s[74:75], v[198:199] op_sel_hi:[1,0,0]
	v_pk_fma_f32 v[178:179], v[172:173], s[74:75], v[198:199] op_sel_hi:[1,0,0]
	v_pk_fma_f32 v[184:185], v[182:183], s[74:75], v[198:199] op_sel_hi:[1,0,0]
	v_pk_fma_f32 v[162:163], v[160:161], v[162:163], s[2:3] op_sel_hi:[1,1,0]
	v_pk_fma_f32 v[168:169], v[166:167], v[168:169], s[2:3] op_sel_hi:[1,1,0]
	v_pk_fma_f32 v[178:179], v[172:173], v[178:179], s[2:3] op_sel_hi:[1,1,0]
	v_pk_fma_f32 v[184:185], v[182:183], v[184:185], s[2:3] op_sel_hi:[1,1,0]
	v_pk_fma_f32 v[162:163], v[160:161], v[162:163], s[28:29] op_sel_hi:[1,1,0]
	v_pk_fma_f32 v[168:169], v[166:167], v[168:169], s[28:29] op_sel_hi:[1,1,0]
	v_pk_fma_f32 v[178:179], v[172:173], v[178:179], s[28:29] op_sel_hi:[1,1,0]
	v_pk_fma_f32 v[184:185], v[182:183], v[184:185], s[28:29] op_sel_hi:[1,1,0]
	v_pk_fma_f32 v[162:163], v[160:161], v[162:163], s[30:31] op_sel_hi:[1,1,0]
	v_pk_fma_f32 v[168:169], v[166:167], v[168:169], s[30:31] op_sel_hi:[1,1,0]
	v_pk_fma_f32 v[178:179], v[172:173], v[178:179], s[30:31] op_sel_hi:[1,1,0]
	v_pk_fma_f32 v[184:185], v[182:183], v[184:185], s[30:31] op_sel_hi:[1,1,0]
	v_pk_fma_f32 v[162:163], v[160:161], v[162:163], s[48:49] op_sel_hi:[1,1,0]
	v_pk_fma_f32 v[168:169], v[166:167], v[168:169], s[48:49] op_sel_hi:[1,1,0]
	v_pk_fma_f32 v[178:179], v[172:173], v[178:179], s[48:49] op_sel_hi:[1,1,0]
	v_pk_fma_f32 v[184:185], v[182:183], v[184:185], s[48:49] op_sel_hi:[1,1,0]
	v_pk_fma_f32 v[162:163], v[160:161], v[162:163], s[50:51] op_sel_hi:[1,1,0]
	v_pk_fma_f32 v[168:169], v[166:167], v[168:169], s[50:51] op_sel_hi:[1,1,0]
	v_pk_fma_f32 v[178:179], v[172:173], v[178:179], s[50:51] op_sel_hi:[1,1,0]
	v_pk_fma_f32 v[184:185], v[182:183], v[184:185], s[50:51] op_sel_hi:[1,1,0]
	v_pk_fma_f32 v[162:163], v[160:161], v[162:163], s[52:53] op_sel_hi:[1,1,0]
	v_pk_fma_f32 v[168:169], v[166:167], v[168:169], s[52:53] op_sel_hi:[1,1,0]
	v_pk_fma_f32 v[178:179], v[172:173], v[178:179], s[52:53] op_sel_hi:[1,1,0]
	v_pk_fma_f32 v[184:185], v[182:183], v[184:185], s[52:53] op_sel_hi:[1,1,0]
	v_pk_fma_f32 v[160:161], v[160:161], v[162:163], s[54:55] op_sel_hi:[1,1,0]
	v_pk_fma_f32 v[166:167], v[166:167], v[168:169], s[54:55] op_sel_hi:[1,1,0]
	v_pk_fma_f32 v[172:173], v[172:173], v[178:179], s[54:55] op_sel_hi:[1,1,0]
	v_pk_fma_f32 v[182:183], v[182:183], v[184:185], s[54:55] op_sel_hi:[1,1,0]
	v_pk_fma_f32 v[158:159], v[158:159], v[160:161], 0.5 op_sel_hi:[1,1,0]
	v_pk_fma_f32 v[164:165], v[164:165], v[166:167], 0.5 op_sel_hi:[1,1,0]
	v_pk_fma_f32 v[170:171], v[170:171], v[172:173], 0.5 op_sel_hi:[1,1,0]
	v_pk_fma_f32 v[180:181], v[180:181], v[182:183], 0.5 op_sel_hi:[1,1,0]
	v_pk_mul_f32 v[124:125], v[124:125], v[158:159]
	v_pk_mul_f32 v[126:127], v[126:127], v[164:165]
	v_pk_mul_f32 v[116:117], v[116:117], v[170:171]
	v_pk_mul_f32 v[118:119], v[118:119], v[180:181]
	v_pk_add_f32 v[158:159], v[128:129], v[130:131]
	v_pk_add_f32 v[160:161], v[120:121], v[122:123]
	v_pk_add_f32 v[162:163], v[124:125], v[126:127]
	v_pk_add_f32 v[164:165], v[116:117], v[118:119]
	v_pk_mul_f32 v[166:167], v[128:129], v[128:129]
	v_pk_mul_f32 v[168:169], v[120:121], v[120:121]
	v_pk_mul_f32 v[170:171], v[124:125], v[124:125]
	v_pk_mul_f32 v[172:173], v[116:117], v[116:117]
	v_pk_fma_f32 v[166:167], v[130:131], v[130:131], v[166:167]
	v_pk_fma_f32 v[168:169], v[122:123], v[122:123], v[168:169]
	v_pk_fma_f32 v[170:171], v[126:127], v[126:127], v[170:171]
	v_pk_fma_f32 v[172:173], v[118:119], v[118:119], v[172:173]
	v_pk_add_f32 v[158:159], v[158:159], v[160:161]
	v_pk_add_f32 v[162:163], v[162:163], v[164:165]
	v_pk_add_f32 v[166:167], v[166:167], v[168:169]
	v_pk_add_f32 v[170:171], v[170:171], v[172:173]
	v_pk_add_f32 v[158:159], v[158:159], v[162:163]
	v_pk_add_f32 v[166:167], v[166:167], v[170:171]
	v_cvt_pk_bf16_f32 v128, v128, v129
	v_cvt_pk_bf16_f32 v129, v130, v131
	v_cvt_pk_bf16_f32 v130, v120, v121
	v_cvt_pk_bf16_f32 v131, v122, v123
	global_store_dwordx4 v201, v[128:131], s[12:13]
	v_cvt_pk_bf16_f32 v124, v124, v125
	v_cvt_pk_bf16_f32 v125, v126, v127
	v_cvt_pk_bf16_f32 v126, v116, v117
	v_cvt_pk_bf16_f32 v127, v118, v119
	global_store_dwordx4 v201, v[124:127], s[12:13] offset:256
	v_add_f32_e32 v120, v158, v159
	v_add_f32_e32 v121, v166, v167
	v_pk_mul_f32 v[112:113], v[112:113], v[238:239] op_sel_hi:[1,0]
	v_pk_mul_f32 v[114:115], v[114:115], v[238:239] op_sel_hi:[1,0]
	v_pk_mul_f32 v[104:105], v[104:105], v[238:239] op_sel_hi:[1,0]
	v_pk_mul_f32 v[106:107], v[106:107], v[238:239] op_sel_hi:[1,0]
	v_pk_mul_f32 v[108:109], v[108:109], v[238:239] op_sel_hi:[1,0]
	v_pk_mul_f32 v[110:111], v[110:111], v[238:239] op_sel_hi:[1,0]
	v_pk_mul_f32 v[100:101], v[100:101], v[238:239] op_sel_hi:[1,0]
	v_pk_mul_f32 v[102:103], v[102:103], v[238:239] op_sel_hi:[1,0]
	v_med3_f32 v158, v112, -4.0, 4.0
	v_med3_f32 v164, v114, -4.0, 4.0
	v_med3_f32 v170, v104, -4.0, 4.0
	v_med3_f32 v180, v106, -4.0, 4.0
	v_med3_f32 v159, v113, -4.0, 4.0
	v_med3_f32 v165, v115, -4.0, 4.0
	v_med3_f32 v171, v105, -4.0, 4.0
	v_med3_f32 v181, v107, -4.0, 4.0
	v_pk_mul_f32 v[160:161], v[158:159], v[158:159]
	v_pk_mul_f32 v[166:167], v[164:165], v[164:165]
	v_pk_mul_f32 v[172:173], v[170:171], v[170:171]
	v_pk_mul_f32 v[182:183], v[180:181], v[180:181]
	v_pk_fma_f32 v[160:161], v[160:161], s[72:73], -1.0 op_sel_hi:[1,0,0]
	v_pk_fma_f32 v[166:167], v[166:167], s[72:73], -1.0 op_sel_hi:[1,0,0]
	v_pk_fma_f32 v[172:173], v[172:173], s[72:73], -1.0 op_sel_hi:[1,0,0]
	v_pk_fma_f32 v[182:183], v[182:183], s[72:73], -1.0 op_sel_hi:[1,0,0]
	v_pk_fma_f32 v[162:163], v[160:161], s[74:75], v[198:199] op_sel_hi:[1,0,0]
	v_pk_fma_f32 v[168:169], v[166:167], s[74:75], v[198:199] op_sel_hi:[1,0,0]
	v_pk_fma_f32 v[178:179], v[172:173], s[74:75], v[198:199] op_sel_hi:[1,0,0]
	v_pk_fma_f32 v[184:185], v[182:183], s[74:75], v[198:199] op_sel_hi:[1,0,0]
	v_pk_fma_f32 v[162:163], v[160:161], v[162:163], s[2:3] op_sel_hi:[1,1,0]
	v_pk_fma_f32 v[168:169], v[166:167], v[168:169], s[2:3] op_sel_hi:[1,1,0]
	v_pk_fma_f32 v[178:179], v[172:173], v[178:179], s[2:3] op_sel_hi:[1,1,0]
	v_pk_fma_f32 v[184:185], v[182:183], v[184:185], s[2:3] op_sel_hi:[1,1,0]
	v_pk_fma_f32 v[162:163], v[160:161], v[162:163], s[28:29] op_sel_hi:[1,1,0]
	v_pk_fma_f32 v[168:169], v[166:167], v[168:169], s[28:29] op_sel_hi:[1,1,0]
	v_pk_fma_f32 v[178:179], v[172:173], v[178:179], s[28:29] op_sel_hi:[1,1,0]
	v_pk_fma_f32 v[184:185], v[182:183], v[184:185], s[28:29] op_sel_hi:[1,1,0]
	v_pk_fma_f32 v[162:163], v[160:161], v[162:163], s[30:31] op_sel_hi:[1,1,0]
	v_pk_fma_f32 v[168:169], v[166:167], v[168:169], s[30:31] op_sel_hi:[1,1,0]
	v_pk_fma_f32 v[178:179], v[172:173], v[178:179], s[30:31] op_sel_hi:[1,1,0]
	v_pk_fma_f32 v[184:185], v[182:183], v[184:185], s[30:31] op_sel_hi:[1,1,0]
	v_pk_fma_f32 v[162:163], v[160:161], v[162:163], s[48:49] op_sel_hi:[1,1,0]
	v_pk_fma_f32 v[168:169], v[166:167], v[168:169], s[48:49] op_sel_hi:[1,1,0]
	v_pk_fma_f32 v[178:179], v[172:173], v[178:179], s[48:49] op_sel_hi:[1,1,0]
	v_pk_fma_f32 v[184:185], v[182:183], v[184:185], s[48:49] op_sel_hi:[1,1,0]
	v_pk_fma_f32 v[162:163], v[160:161], v[162:163], s[50:51] op_sel_hi:[1,1,0]
	v_pk_fma_f32 v[168:169], v[166:167], v[168:169], s[50:51] op_sel_hi:[1,1,0]
	v_pk_fma_f32 v[178:179], v[172:173], v[178:179], s[50:51] op_sel_hi:[1,1,0]
	v_pk_fma_f32 v[184:185], v[182:183], v[184:185], s[50:51] op_sel_hi:[1,1,0]
	v_pk_fma_f32 v[162:163], v[160:161], v[162:163], s[52:53] op_sel_hi:[1,1,0]
	v_pk_fma_f32 v[168:169], v[166:167], v[168:169], s[52:53] op_sel_hi:[1,1,0]
	v_pk_fma_f32 v[178:179], v[172:173], v[178:179], s[52:53] op_sel_hi:[1,1,0]
	v_pk_fma_f32 v[184:185], v[182:183], v[184:185], s[52:53] op_sel_hi:[1,1,0]
	v_pk_fma_f32 v[160:161], v[160:161], v[162:163], s[54:55] op_sel_hi:[1,1,0]
	v_pk_fma_f32 v[166:167], v[166:167], v[168:169], s[54:55] op_sel_hi:[1,1,0]
	v_pk_fma_f32 v[172:173], v[172:173], v[178:179], s[54:55] op_sel_hi:[1,1,0]
	v_pk_fma_f32 v[182:183], v[182:183], v[184:185], s[54:55] op_sel_hi:[1,1,0]
	v_pk_fma_f32 v[158:159], v[158:159], v[160:161], 0.5 op_sel_hi:[1,1,0]
	v_pk_fma_f32 v[164:165], v[164:165], v[166:167], 0.5 op_sel_hi:[1,1,0]
	v_pk_fma_f32 v[170:171], v[170:171], v[172:173], 0.5 op_sel_hi:[1,1,0]
	v_pk_fma_f32 v[180:181], v[180:181], v[182:183], 0.5 op_sel_hi:[1,1,0]
	v_pk_mul_f32 v[112:113], v[112:113], v[158:159]
	v_pk_mul_f32 v[114:115], v[114:115], v[164:165]
	v_pk_mul_f32 v[104:105], v[104:105], v[170:171]
	v_pk_mul_f32 v[106:107], v[106:107], v[180:181]
	v_med3_f32 v158, v108, -4.0, 4.0
	v_med3_f32 v164, v110, -4.0, 4.0
	v_med3_f32 v170, v100, -4.0, 4.0
	v_med3_f32 v180, v102, -4.0, 4.0
	v_med3_f32 v159, v109, -4.0, 4.0
	v_med3_f32 v165, v111, -4.0, 4.0
	v_med3_f32 v171, v101, -4.0, 4.0
	v_med3_f32 v181, v103, -4.0, 4.0
	v_pk_mul_f32 v[160:161], v[158:159], v[158:159]
	v_pk_mul_f32 v[166:167], v[164:165], v[164:165]
	v_pk_mul_f32 v[172:173], v[170:171], v[170:171]
	v_pk_mul_f32 v[182:183], v[180:181], v[180:181]
	v_pk_fma_f32 v[160:161], v[160:161], s[72:73], -1.0 op_sel_hi:[1,0,0]
	v_pk_fma_f32 v[166:167], v[166:167], s[72:73], -1.0 op_sel_hi:[1,0,0]
	v_pk_fma_f32 v[172:173], v[172:173], s[72:73], -1.0 op_sel_hi:[1,0,0]
	v_pk_fma_f32 v[182:183], v[182:183], s[72:73], -1.0 op_sel_hi:[1,0,0]
	v_pk_fma_f32 v[162:163], v[160:161], s[74:75], v[198:199] op_sel_hi:[1,0,0]
	v_pk_fma_f32 v[168:169], v[166:167], s[74:75], v[198:199] op_sel_hi:[1,0,0]
	v_pk_fma_f32 v[178:179], v[172:173], s[74:75], v[198:199] op_sel_hi:[1,0,0]
	v_pk_fma_f32 v[184:185], v[182:183], s[74:75], v[198:199] op_sel_hi:[1,0,0]
	v_pk_fma_f32 v[162:163], v[160:161], v[162:163], s[2:3] op_sel_hi:[1,1,0]
	v_pk_fma_f32 v[168:169], v[166:167], v[168:169], s[2:3] op_sel_hi:[1,1,0]
	v_pk_fma_f32 v[178:179], v[172:173], v[178:179], s[2:3] op_sel_hi:[1,1,0]
	v_pk_fma_f32 v[184:185], v[182:183], v[184:185], s[2:3] op_sel_hi:[1,1,0]
	v_pk_fma_f32 v[162:163], v[160:161], v[162:163], s[28:29] op_sel_hi:[1,1,0]
	v_pk_fma_f32 v[168:169], v[166:167], v[168:169], s[28:29] op_sel_hi:[1,1,0]
	v_pk_fma_f32 v[178:179], v[172:173], v[178:179], s[28:29] op_sel_hi:[1,1,0]
	v_pk_fma_f32 v[184:185], v[182:183], v[184:185], s[28:29] op_sel_hi:[1,1,0]
	v_pk_fma_f32 v[162:163], v[160:161], v[162:163], s[30:31] op_sel_hi:[1,1,0]
	v_pk_fma_f32 v[168:169], v[166:167], v[168:169], s[30:31] op_sel_hi:[1,1,0]
	v_pk_fma_f32 v[178:179], v[172:173], v[178:179], s[30:31] op_sel_hi:[1,1,0]
	v_pk_fma_f32 v[184:185], v[182:183], v[184:185], s[30:31] op_sel_hi:[1,1,0]
	v_pk_fma_f32 v[162:163], v[160:161], v[162:163], s[48:49] op_sel_hi:[1,1,0]
	v_pk_fma_f32 v[168:169], v[166:167], v[168:169], s[48:49] op_sel_hi:[1,1,0]
	v_pk_fma_f32 v[178:179], v[172:173], v[178:179], s[48:49] op_sel_hi:[1,1,0]
	v_pk_fma_f32 v[184:185], v[182:183], v[184:185], s[48:49] op_sel_hi:[1,1,0]
	v_pk_fma_f32 v[162:163], v[160:161], v[162:163], s[50:51] op_sel_hi:[1,1,0]
	v_pk_fma_f32 v[168:169], v[166:167], v[168:169], s[50:51] op_sel_hi:[1,1,0]
	v_pk_fma_f32 v[178:179], v[172:173], v[178:179], s[50:51] op_sel_hi:[1,1,0]
	v_pk_fma_f32 v[184:185], v[182:183], v[184:185], s[50:51] op_sel_hi:[1,1,0]
	v_pk_fma_f32 v[162:163], v[160:161], v[162:163], s[52:53] op_sel_hi:[1,1,0]
	v_pk_fma_f32 v[168:169], v[166:167], v[168:169], s[52:53] op_sel_hi:[1,1,0]
	v_pk_fma_f32 v[178:179], v[172:173], v[178:179], s[52:53] op_sel_hi:[1,1,0]
	v_pk_fma_f32 v[184:185], v[182:183], v[184:185], s[52:53] op_sel_hi:[1,1,0]
	v_pk_fma_f32 v[160:161], v[160:161], v[162:163], s[54:55] op_sel_hi:[1,1,0]
	v_pk_fma_f32 v[166:167], v[166:167], v[168:169], s[54:55] op_sel_hi:[1,1,0]
	v_pk_fma_f32 v[172:173], v[172:173], v[178:179], s[54:55] op_sel_hi:[1,1,0]
	v_pk_fma_f32 v[182:183], v[182:183], v[184:185], s[54:55] op_sel_hi:[1,1,0]
	v_pk_fma_f32 v[158:159], v[158:159], v[160:161], 0.5 op_sel_hi:[1,1,0]
	v_pk_fma_f32 v[164:165], v[164:165], v[166:167], 0.5 op_sel_hi:[1,1,0]
	v_pk_fma_f32 v[170:171], v[170:171], v[172:173], 0.5 op_sel_hi:[1,1,0]
	v_pk_fma_f32 v[180:181], v[180:181], v[182:183], 0.5 op_sel_hi:[1,1,0]
	v_pk_mul_f32 v[108:109], v[108:109], v[158:159]
	v_pk_mul_f32 v[110:111], v[110:111], v[164:165]
	v_pk_mul_f32 v[100:101], v[100:101], v[170:171]
	v_pk_mul_f32 v[102:103], v[102:103], v[180:181]
	v_pk_add_f32 v[158:159], v[112:113], v[114:115]
	v_pk_add_f32 v[160:161], v[104:105], v[106:107]
	v_pk_add_f32 v[162:163], v[108:109], v[110:111]
	v_pk_add_f32 v[164:165], v[100:101], v[102:103]
	v_pk_mul_f32 v[166:167], v[112:113], v[112:113]
	v_pk_mul_f32 v[168:169], v[104:105], v[104:105]
	v_pk_mul_f32 v[170:171], v[108:109], v[108:109]
	v_pk_mul_f32 v[172:173], v[100:101], v[100:101]
	v_pk_fma_f32 v[166:167], v[114:115], v[114:115], v[166:167]
	v_pk_fma_f32 v[168:169], v[106:107], v[106:107], v[168:169]
	v_pk_fma_f32 v[170:171], v[110:111], v[110:111], v[170:171]
	v_pk_fma_f32 v[172:173], v[102:103], v[102:103], v[172:173]
	v_pk_add_f32 v[158:159], v[158:159], v[160:161]
	v_pk_add_f32 v[162:163], v[162:163], v[164:165]
	v_pk_add_f32 v[166:167], v[166:167], v[168:169]
	v_pk_add_f32 v[170:171], v[170:171], v[172:173]
	v_pk_add_f32 v[158:159], v[158:159], v[162:163]
	v_pk_add_f32 v[166:167], v[166:167], v[170:171]
	v_cvt_pk_bf16_f32 v112, v112, v113
	v_cvt_pk_bf16_f32 v113, v114, v115
	v_cvt_pk_bf16_f32 v114, v104, v105
	v_cvt_pk_bf16_f32 v115, v106, v107
	global_store_dwordx4 v203, v[112:115], s[12:13]
	v_cvt_pk_bf16_f32 v108, v108, v109
	v_cvt_pk_bf16_f32 v109, v110, v111
	v_cvt_pk_bf16_f32 v110, v100, v101
	v_cvt_pk_bf16_f32 v111, v102, v103
	global_store_dwordx4 v203, v[108:111], s[12:13] offset:256
	v_add_f32_e32 v104, v158, v159
	v_add_f32_e32 v105, v166, v167
	v_pk_mul_f32 v[96:97], v[96:97], v[240:241] op_sel_hi:[1,0]
	v_pk_mul_f32 v[98:99], v[98:99], v[240:241] op_sel_hi:[1,0]
	v_pk_mul_f32 v[88:89], v[88:89], v[240:241] op_sel_hi:[1,0]
	v_pk_mul_f32 v[90:91], v[90:91], v[240:241] op_sel_hi:[1,0]
	v_pk_mul_f32 v[92:93], v[92:93], v[240:241] op_sel_hi:[1,0]
	v_pk_mul_f32 v[94:95], v[94:95], v[240:241] op_sel_hi:[1,0]
	v_pk_mul_f32 v[84:85], v[84:85], v[240:241] op_sel_hi:[1,0]
	v_pk_mul_f32 v[86:87], v[86:87], v[240:241] op_sel_hi:[1,0]
	v_med3_f32 v158, v96, -4.0, 4.0
	v_med3_f32 v164, v98, -4.0, 4.0
	v_med3_f32 v170, v88, -4.0, 4.0
	v_med3_f32 v180, v90, -4.0, 4.0
	v_med3_f32 v159, v97, -4.0, 4.0
	v_med3_f32 v165, v99, -4.0, 4.0
	v_med3_f32 v171, v89, -4.0, 4.0
	v_med3_f32 v181, v91, -4.0, 4.0
	v_pk_mul_f32 v[160:161], v[158:159], v[158:159]
	v_pk_mul_f32 v[166:167], v[164:165], v[164:165]
	v_pk_mul_f32 v[172:173], v[170:171], v[170:171]
	v_pk_mul_f32 v[182:183], v[180:181], v[180:181]
	v_pk_fma_f32 v[160:161], v[160:161], s[72:73], -1.0 op_sel_hi:[1,0,0]
	v_pk_fma_f32 v[166:167], v[166:167], s[72:73], -1.0 op_sel_hi:[1,0,0]
	v_pk_fma_f32 v[172:173], v[172:173], s[72:73], -1.0 op_sel_hi:[1,0,0]
	v_pk_fma_f32 v[182:183], v[182:183], s[72:73], -1.0 op_sel_hi:[1,0,0]
	v_pk_fma_f32 v[162:163], v[160:161], s[74:75], v[198:199] op_sel_hi:[1,0,0]
	v_pk_fma_f32 v[168:169], v[166:167], s[74:75], v[198:199] op_sel_hi:[1,0,0]
	v_pk_fma_f32 v[178:179], v[172:173], s[74:75], v[198:199] op_sel_hi:[1,0,0]
	v_pk_fma_f32 v[184:185], v[182:183], s[74:75], v[198:199] op_sel_hi:[1,0,0]
	v_pk_fma_f32 v[162:163], v[160:161], v[162:163], s[2:3] op_sel_hi:[1,1,0]
	v_pk_fma_f32 v[168:169], v[166:167], v[168:169], s[2:3] op_sel_hi:[1,1,0]
	v_pk_fma_f32 v[178:179], v[172:173], v[178:179], s[2:3] op_sel_hi:[1,1,0]
	v_pk_fma_f32 v[184:185], v[182:183], v[184:185], s[2:3] op_sel_hi:[1,1,0]
	v_pk_fma_f32 v[162:163], v[160:161], v[162:163], s[28:29] op_sel_hi:[1,1,0]
	v_pk_fma_f32 v[168:169], v[166:167], v[168:169], s[28:29] op_sel_hi:[1,1,0]
	v_pk_fma_f32 v[178:179], v[172:173], v[178:179], s[28:29] op_sel_hi:[1,1,0]
	v_pk_fma_f32 v[184:185], v[182:183], v[184:185], s[28:29] op_sel_hi:[1,1,0]
	v_pk_fma_f32 v[162:163], v[160:161], v[162:163], s[30:31] op_sel_hi:[1,1,0]
	v_pk_fma_f32 v[168:169], v[166:167], v[168:169], s[30:31] op_sel_hi:[1,1,0]
	v_pk_fma_f32 v[178:179], v[172:173], v[178:179], s[30:31] op_sel_hi:[1,1,0]
	v_pk_fma_f32 v[184:185], v[182:183], v[184:185], s[30:31] op_sel_hi:[1,1,0]
	v_pk_fma_f32 v[162:163], v[160:161], v[162:163], s[48:49] op_sel_hi:[1,1,0]
	v_pk_fma_f32 v[168:169], v[166:167], v[168:169], s[48:49] op_sel_hi:[1,1,0]
	v_pk_fma_f32 v[178:179], v[172:173], v[178:179], s[48:49] op_sel_hi:[1,1,0]
	v_pk_fma_f32 v[184:185], v[182:183], v[184:185], s[48:49] op_sel_hi:[1,1,0]
	v_pk_fma_f32 v[162:163], v[160:161], v[162:163], s[50:51] op_sel_hi:[1,1,0]
	v_pk_fma_f32 v[168:169], v[166:167], v[168:169], s[50:51] op_sel_hi:[1,1,0]
	v_pk_fma_f32 v[178:179], v[172:173], v[178:179], s[50:51] op_sel_hi:[1,1,0]
	v_pk_fma_f32 v[184:185], v[182:183], v[184:185], s[50:51] op_sel_hi:[1,1,0]
	v_pk_fma_f32 v[162:163], v[160:161], v[162:163], s[52:53] op_sel_hi:[1,1,0]
	v_pk_fma_f32 v[168:169], v[166:167], v[168:169], s[52:53] op_sel_hi:[1,1,0]
	v_pk_fma_f32 v[178:179], v[172:173], v[178:179], s[52:53] op_sel_hi:[1,1,0]
	v_pk_fma_f32 v[184:185], v[182:183], v[184:185], s[52:53] op_sel_hi:[1,1,0]
	v_pk_fma_f32 v[160:161], v[160:161], v[162:163], s[54:55] op_sel_hi:[1,1,0]
	v_pk_fma_f32 v[166:167], v[166:167], v[168:169], s[54:55] op_sel_hi:[1,1,0]
	v_pk_fma_f32 v[172:173], v[172:173], v[178:179], s[54:55] op_sel_hi:[1,1,0]
	v_pk_fma_f32 v[182:183], v[182:183], v[184:185], s[54:55] op_sel_hi:[1,1,0]
	v_pk_fma_f32 v[158:159], v[158:159], v[160:161], 0.5 op_sel_hi:[1,1,0]
	v_pk_fma_f32 v[164:165], v[164:165], v[166:167], 0.5 op_sel_hi:[1,1,0]
	v_pk_fma_f32 v[170:171], v[170:171], v[172:173], 0.5 op_sel_hi:[1,1,0]
	v_pk_fma_f32 v[180:181], v[180:181], v[182:183], 0.5 op_sel_hi:[1,1,0]
	v_pk_mul_f32 v[96:97], v[96:97], v[158:159]
	v_pk_mul_f32 v[98:99], v[98:99], v[164:165]
	v_pk_mul_f32 v[88:89], v[88:89], v[170:171]
	v_pk_mul_f32 v[90:91], v[90:91], v[180:181]
	v_med3_f32 v158, v92, -4.0, 4.0
	v_med3_f32 v164, v94, -4.0, 4.0
	v_med3_f32 v170, v84, -4.0, 4.0
	v_med3_f32 v180, v86, -4.0, 4.0
	v_med3_f32 v159, v93, -4.0, 4.0
	v_med3_f32 v165, v95, -4.0, 4.0
	v_med3_f32 v171, v85, -4.0, 4.0
	v_med3_f32 v181, v87, -4.0, 4.0
	v_pk_mul_f32 v[160:161], v[158:159], v[158:159]
	v_pk_mul_f32 v[166:167], v[164:165], v[164:165]
	v_pk_mul_f32 v[172:173], v[170:171], v[170:171]
	v_pk_mul_f32 v[182:183], v[180:181], v[180:181]
	v_pk_fma_f32 v[160:161], v[160:161], s[72:73], -1.0 op_sel_hi:[1,0,0]
	v_pk_fma_f32 v[166:167], v[166:167], s[72:73], -1.0 op_sel_hi:[1,0,0]
	v_pk_fma_f32 v[172:173], v[172:173], s[72:73], -1.0 op_sel_hi:[1,0,0]
	v_pk_fma_f32 v[182:183], v[182:183], s[72:73], -1.0 op_sel_hi:[1,0,0]
	v_pk_fma_f32 v[162:163], v[160:161], s[74:75], v[198:199] op_sel_hi:[1,0,0]
	v_pk_fma_f32 v[168:169], v[166:167], s[74:75], v[198:199] op_sel_hi:[1,0,0]
	v_pk_fma_f32 v[178:179], v[172:173], s[74:75], v[198:199] op_sel_hi:[1,0,0]
	v_pk_fma_f32 v[184:185], v[182:183], s[74:75], v[198:199] op_sel_hi:[1,0,0]
	v_pk_fma_f32 v[162:163], v[160:161], v[162:163], s[2:3] op_sel_hi:[1,1,0]
	v_pk_fma_f32 v[168:169], v[166:167], v[168:169], s[2:3] op_sel_hi:[1,1,0]
	v_pk_fma_f32 v[178:179], v[172:173], v[178:179], s[2:3] op_sel_hi:[1,1,0]
	v_pk_fma_f32 v[184:185], v[182:183], v[184:185], s[2:3] op_sel_hi:[1,1,0]
	v_pk_fma_f32 v[162:163], v[160:161], v[162:163], s[28:29] op_sel_hi:[1,1,0]
	v_pk_fma_f32 v[168:169], v[166:167], v[168:169], s[28:29] op_sel_hi:[1,1,0]
	v_pk_fma_f32 v[178:179], v[172:173], v[178:179], s[28:29] op_sel_hi:[1,1,0]
	v_pk_fma_f32 v[184:185], v[182:183], v[184:185], s[28:29] op_sel_hi:[1,1,0]
	v_pk_fma_f32 v[162:163], v[160:161], v[162:163], s[30:31] op_sel_hi:[1,1,0]
	v_pk_fma_f32 v[168:169], v[166:167], v[168:169], s[30:31] op_sel_hi:[1,1,0]
	v_pk_fma_f32 v[178:179], v[172:173], v[178:179], s[30:31] op_sel_hi:[1,1,0]
	v_pk_fma_f32 v[184:185], v[182:183], v[184:185], s[30:31] op_sel_hi:[1,1,0]
	v_pk_fma_f32 v[162:163], v[160:161], v[162:163], s[48:49] op_sel_hi:[1,1,0]
	v_pk_fma_f32 v[168:169], v[166:167], v[168:169], s[48:49] op_sel_hi:[1,1,0]
	v_pk_fma_f32 v[178:179], v[172:173], v[178:179], s[48:49] op_sel_hi:[1,1,0]
	v_pk_fma_f32 v[184:185], v[182:183], v[184:185], s[48:49] op_sel_hi:[1,1,0]
	v_pk_fma_f32 v[162:163], v[160:161], v[162:163], s[50:51] op_sel_hi:[1,1,0]
	v_pk_fma_f32 v[168:169], v[166:167], v[168:169], s[50:51] op_sel_hi:[1,1,0]
	v_pk_fma_f32 v[178:179], v[172:173], v[178:179], s[50:51] op_sel_hi:[1,1,0]
	v_pk_fma_f32 v[184:185], v[182:183], v[184:185], s[50:51] op_sel_hi:[1,1,0]
	v_pk_fma_f32 v[162:163], v[160:161], v[162:163], s[52:53] op_sel_hi:[1,1,0]
	v_pk_fma_f32 v[168:169], v[166:167], v[168:169], s[52:53] op_sel_hi:[1,1,0]
	v_pk_fma_f32 v[178:179], v[172:173], v[178:179], s[52:53] op_sel_hi:[1,1,0]
	v_pk_fma_f32 v[184:185], v[182:183], v[184:185], s[52:53] op_sel_hi:[1,1,0]
	v_pk_fma_f32 v[160:161], v[160:161], v[162:163], s[54:55] op_sel_hi:[1,1,0]
	v_pk_fma_f32 v[166:167], v[166:167], v[168:169], s[54:55] op_sel_hi:[1,1,0]
	v_pk_fma_f32 v[172:173], v[172:173], v[178:179], s[54:55] op_sel_hi:[1,1,0]
	v_pk_fma_f32 v[182:183], v[182:183], v[184:185], s[54:55] op_sel_hi:[1,1,0]
	v_pk_fma_f32 v[158:159], v[158:159], v[160:161], 0.5 op_sel_hi:[1,1,0]
	v_pk_fma_f32 v[164:165], v[164:165], v[166:167], 0.5 op_sel_hi:[1,1,0]
	v_pk_fma_f32 v[170:171], v[170:171], v[172:173], 0.5 op_sel_hi:[1,1,0]
	v_pk_fma_f32 v[180:181], v[180:181], v[182:183], 0.5 op_sel_hi:[1,1,0]
	v_pk_mul_f32 v[92:93], v[92:93], v[158:159]
	v_pk_mul_f32 v[94:95], v[94:95], v[164:165]
	v_pk_mul_f32 v[84:85], v[84:85], v[170:171]
	v_pk_mul_f32 v[86:87], v[86:87], v[180:181]
	v_pk_add_f32 v[158:159], v[96:97], v[98:99]
	v_pk_add_f32 v[160:161], v[88:89], v[90:91]
	v_pk_add_f32 v[162:163], v[92:93], v[94:95]
	v_pk_add_f32 v[164:165], v[84:85], v[86:87]
	v_pk_mul_f32 v[166:167], v[96:97], v[96:97]
	v_pk_mul_f32 v[168:169], v[88:89], v[88:89]
	v_pk_mul_f32 v[170:171], v[92:93], v[92:93]
	v_pk_mul_f32 v[172:173], v[84:85], v[84:85]
	v_pk_fma_f32 v[166:167], v[98:99], v[98:99], v[166:167]
	v_pk_fma_f32 v[168:169], v[90:91], v[90:91], v[168:169]
	v_pk_fma_f32 v[170:171], v[94:95], v[94:95], v[170:171]
	v_pk_fma_f32 v[172:173], v[86:87], v[86:87], v[172:173]
	v_pk_add_f32 v[158:159], v[158:159], v[160:161]
	v_pk_add_f32 v[162:163], v[162:163], v[164:165]
	v_pk_add_f32 v[166:167], v[166:167], v[168:169]
	v_pk_add_f32 v[170:171], v[170:171], v[172:173]
	v_pk_add_f32 v[158:159], v[158:159], v[162:163]
	v_pk_add_f32 v[166:167], v[166:167], v[170:171]
	v_cvt_pk_bf16_f32 v96, v96, v97
	v_cvt_pk_bf16_f32 v97, v98, v99
	v_cvt_pk_bf16_f32 v98, v88, v89
	v_cvt_pk_bf16_f32 v99, v90, v91
	global_store_dwordx4 v205, v[96:99], s[12:13]
	v_cvt_pk_bf16_f32 v92, v92, v93
	v_cvt_pk_bf16_f32 v93, v94, v95
	v_cvt_pk_bf16_f32 v94, v84, v85
	v_cvt_pk_bf16_f32 v95, v86, v87
	global_store_dwordx4 v205, v[92:95], s[12:13] offset:256
	v_add_f32_e32 v88, v158, v159
	v_add_f32_e32 v89, v166, v167
	v_pk_mul_f32 v[80:81], v[80:81], v[242:243] op_sel_hi:[1,0]
	v_pk_mul_f32 v[82:83], v[82:83], v[242:243] op_sel_hi:[1,0]
	v_pk_mul_f32 v[72:73], v[72:73], v[242:243] op_sel_hi:[1,0]
	v_pk_mul_f32 v[74:75], v[74:75], v[242:243] op_sel_hi:[1,0]
	v_pk_mul_f32 v[76:77], v[76:77], v[242:243] op_sel_hi:[1,0]
	v_pk_mul_f32 v[78:79], v[78:79], v[242:243] op_sel_hi:[1,0]
	v_pk_mul_f32 v[68:69], v[68:69], v[242:243] op_sel_hi:[1,0]
	v_pk_mul_f32 v[70:71], v[70:71], v[242:243] op_sel_hi:[1,0]
	v_med3_f32 v158, v80, -4.0, 4.0
	v_med3_f32 v164, v82, -4.0, 4.0
	v_med3_f32 v170, v72, -4.0, 4.0
	v_med3_f32 v180, v74, -4.0, 4.0
	v_med3_f32 v159, v81, -4.0, 4.0
	v_med3_f32 v165, v83, -4.0, 4.0
	v_med3_f32 v171, v73, -4.0, 4.0
	v_med3_f32 v181, v75, -4.0, 4.0
	v_pk_mul_f32 v[160:161], v[158:159], v[158:159]
	v_pk_mul_f32 v[166:167], v[164:165], v[164:165]
	v_pk_mul_f32 v[172:173], v[170:171], v[170:171]
	v_pk_mul_f32 v[182:183], v[180:181], v[180:181]
	v_pk_fma_f32 v[160:161], v[160:161], s[72:73], -1.0 op_sel_hi:[1,0,0]
	v_pk_fma_f32 v[166:167], v[166:167], s[72:73], -1.0 op_sel_hi:[1,0,0]
	v_pk_fma_f32 v[172:173], v[172:173], s[72:73], -1.0 op_sel_hi:[1,0,0]
	v_pk_fma_f32 v[182:183], v[182:183], s[72:73], -1.0 op_sel_hi:[1,0,0]
	v_pk_fma_f32 v[162:163], v[160:161], s[74:75], v[198:199] op_sel_hi:[1,0,0]
	v_pk_fma_f32 v[168:169], v[166:167], s[74:75], v[198:199] op_sel_hi:[1,0,0]
	v_pk_fma_f32 v[178:179], v[172:173], s[74:75], v[198:199] op_sel_hi:[1,0,0]
	v_pk_fma_f32 v[184:185], v[182:183], s[74:75], v[198:199] op_sel_hi:[1,0,0]
	v_pk_fma_f32 v[162:163], v[160:161], v[162:163], s[2:3] op_sel_hi:[1,1,0]
	v_pk_fma_f32 v[168:169], v[166:167], v[168:169], s[2:3] op_sel_hi:[1,1,0]
	v_pk_fma_f32 v[178:179], v[172:173], v[178:179], s[2:3] op_sel_hi:[1,1,0]
	v_pk_fma_f32 v[184:185], v[182:183], v[184:185], s[2:3] op_sel_hi:[1,1,0]
	v_pk_fma_f32 v[162:163], v[160:161], v[162:163], s[28:29] op_sel_hi:[1,1,0]
	v_pk_fma_f32 v[168:169], v[166:167], v[168:169], s[28:29] op_sel_hi:[1,1,0]
	v_pk_fma_f32 v[178:179], v[172:173], v[178:179], s[28:29] op_sel_hi:[1,1,0]
	v_pk_fma_f32 v[184:185], v[182:183], v[184:185], s[28:29] op_sel_hi:[1,1,0]
	v_pk_fma_f32 v[162:163], v[160:161], v[162:163], s[30:31] op_sel_hi:[1,1,0]
	v_pk_fma_f32 v[168:169], v[166:167], v[168:169], s[30:31] op_sel_hi:[1,1,0]
	v_pk_fma_f32 v[178:179], v[172:173], v[178:179], s[30:31] op_sel_hi:[1,1,0]
	v_pk_fma_f32 v[184:185], v[182:183], v[184:185], s[30:31] op_sel_hi:[1,1,0]
	v_pk_fma_f32 v[162:163], v[160:161], v[162:163], s[48:49] op_sel_hi:[1,1,0]
	v_pk_fma_f32 v[168:169], v[166:167], v[168:169], s[48:49] op_sel_hi:[1,1,0]
	v_pk_fma_f32 v[178:179], v[172:173], v[178:179], s[48:49] op_sel_hi:[1,1,0]
	v_pk_fma_f32 v[184:185], v[182:183], v[184:185], s[48:49] op_sel_hi:[1,1,0]
	v_pk_fma_f32 v[162:163], v[160:161], v[162:163], s[50:51] op_sel_hi:[1,1,0]
	v_pk_fma_f32 v[168:169], v[166:167], v[168:169], s[50:51] op_sel_hi:[1,1,0]
	v_pk_fma_f32 v[178:179], v[172:173], v[178:179], s[50:51] op_sel_hi:[1,1,0]
	v_pk_fma_f32 v[184:185], v[182:183], v[184:185], s[50:51] op_sel_hi:[1,1,0]
	v_pk_fma_f32 v[162:163], v[160:161], v[162:163], s[52:53] op_sel_hi:[1,1,0]
	v_pk_fma_f32 v[168:169], v[166:167], v[168:169], s[52:53] op_sel_hi:[1,1,0]
	v_pk_fma_f32 v[178:179], v[172:173], v[178:179], s[52:53] op_sel_hi:[1,1,0]
	v_pk_fma_f32 v[184:185], v[182:183], v[184:185], s[52:53] op_sel_hi:[1,1,0]
	v_pk_fma_f32 v[160:161], v[160:161], v[162:163], s[54:55] op_sel_hi:[1,1,0]
	v_pk_fma_f32 v[166:167], v[166:167], v[168:169], s[54:55] op_sel_hi:[1,1,0]
	v_pk_fma_f32 v[172:173], v[172:173], v[178:179], s[54:55] op_sel_hi:[1,1,0]
	v_pk_fma_f32 v[182:183], v[182:183], v[184:185], s[54:55] op_sel_hi:[1,1,0]
	v_pk_fma_f32 v[158:159], v[158:159], v[160:161], 0.5 op_sel_hi:[1,1,0]
	v_pk_fma_f32 v[164:165], v[164:165], v[166:167], 0.5 op_sel_hi:[1,1,0]
	v_pk_fma_f32 v[170:171], v[170:171], v[172:173], 0.5 op_sel_hi:[1,1,0]
	v_pk_fma_f32 v[180:181], v[180:181], v[182:183], 0.5 op_sel_hi:[1,1,0]
	v_pk_mul_f32 v[80:81], v[80:81], v[158:159]
	v_pk_mul_f32 v[82:83], v[82:83], v[164:165]
	v_pk_mul_f32 v[72:73], v[72:73], v[170:171]
	v_pk_mul_f32 v[74:75], v[74:75], v[180:181]
	v_med3_f32 v158, v76, -4.0, 4.0
	v_med3_f32 v164, v78, -4.0, 4.0
	v_med3_f32 v170, v68, -4.0, 4.0
	v_med3_f32 v180, v70, -4.0, 4.0
	v_med3_f32 v159, v77, -4.0, 4.0
	v_med3_f32 v165, v79, -4.0, 4.0
	v_med3_f32 v171, v69, -4.0, 4.0
	v_med3_f32 v181, v71, -4.0, 4.0
	v_pk_mul_f32 v[160:161], v[158:159], v[158:159]
	v_pk_mul_f32 v[166:167], v[164:165], v[164:165]
	v_pk_mul_f32 v[172:173], v[170:171], v[170:171]
	v_pk_mul_f32 v[182:183], v[180:181], v[180:181]
	v_pk_fma_f32 v[160:161], v[160:161], s[72:73], -1.0 op_sel_hi:[1,0,0]
	v_pk_fma_f32 v[166:167], v[166:167], s[72:73], -1.0 op_sel_hi:[1,0,0]
	v_pk_fma_f32 v[172:173], v[172:173], s[72:73], -1.0 op_sel_hi:[1,0,0]
	v_pk_fma_f32 v[182:183], v[182:183], s[72:73], -1.0 op_sel_hi:[1,0,0]
	v_pk_fma_f32 v[162:163], v[160:161], s[74:75], v[198:199] op_sel_hi:[1,0,0]
	v_pk_fma_f32 v[168:169], v[166:167], s[74:75], v[198:199] op_sel_hi:[1,0,0]
	v_pk_fma_f32 v[178:179], v[172:173], s[74:75], v[198:199] op_sel_hi:[1,0,0]
	v_pk_fma_f32 v[184:185], v[182:183], s[74:75], v[198:199] op_sel_hi:[1,0,0]
	v_pk_fma_f32 v[162:163], v[160:161], v[162:163], s[2:3] op_sel_hi:[1,1,0]
	v_pk_fma_f32 v[168:169], v[166:167], v[168:169], s[2:3] op_sel_hi:[1,1,0]
	v_pk_fma_f32 v[178:179], v[172:173], v[178:179], s[2:3] op_sel_hi:[1,1,0]
	v_pk_fma_f32 v[184:185], v[182:183], v[184:185], s[2:3] op_sel_hi:[1,1,0]
	v_pk_fma_f32 v[162:163], v[160:161], v[162:163], s[28:29] op_sel_hi:[1,1,0]
	v_pk_fma_f32 v[168:169], v[166:167], v[168:169], s[28:29] op_sel_hi:[1,1,0]
	v_pk_fma_f32 v[178:179], v[172:173], v[178:179], s[28:29] op_sel_hi:[1,1,0]
	v_pk_fma_f32 v[184:185], v[182:183], v[184:185], s[28:29] op_sel_hi:[1,1,0]
	v_pk_fma_f32 v[162:163], v[160:161], v[162:163], s[30:31] op_sel_hi:[1,1,0]
	v_pk_fma_f32 v[168:169], v[166:167], v[168:169], s[30:31] op_sel_hi:[1,1,0]
	v_pk_fma_f32 v[178:179], v[172:173], v[178:179], s[30:31] op_sel_hi:[1,1,0]
	v_pk_fma_f32 v[184:185], v[182:183], v[184:185], s[30:31] op_sel_hi:[1,1,0]
	v_pk_fma_f32 v[162:163], v[160:161], v[162:163], s[48:49] op_sel_hi:[1,1,0]
	v_pk_fma_f32 v[168:169], v[166:167], v[168:169], s[48:49] op_sel_hi:[1,1,0]
	v_pk_fma_f32 v[178:179], v[172:173], v[178:179], s[48:49] op_sel_hi:[1,1,0]
	v_pk_fma_f32 v[184:185], v[182:183], v[184:185], s[48:49] op_sel_hi:[1,1,0]
	v_pk_fma_f32 v[162:163], v[160:161], v[162:163], s[50:51] op_sel_hi:[1,1,0]
	v_pk_fma_f32 v[168:169], v[166:167], v[168:169], s[50:51] op_sel_hi:[1,1,0]
	v_pk_fma_f32 v[178:179], v[172:173], v[178:179], s[50:51] op_sel_hi:[1,1,0]
	v_pk_fma_f32 v[184:185], v[182:183], v[184:185], s[50:51] op_sel_hi:[1,1,0]
	v_pk_fma_f32 v[162:163], v[160:161], v[162:163], s[52:53] op_sel_hi:[1,1,0]
	v_pk_fma_f32 v[168:169], v[166:167], v[168:169], s[52:53] op_sel_hi:[1,1,0]
	v_pk_fma_f32 v[178:179], v[172:173], v[178:179], s[52:53] op_sel_hi:[1,1,0]
	v_pk_fma_f32 v[184:185], v[182:183], v[184:185], s[52:53] op_sel_hi:[1,1,0]
	v_pk_fma_f32 v[160:161], v[160:161], v[162:163], s[54:55] op_sel_hi:[1,1,0]
	v_pk_fma_f32 v[166:167], v[166:167], v[168:169], s[54:55] op_sel_hi:[1,1,0]
	v_pk_fma_f32 v[172:173], v[172:173], v[178:179], s[54:55] op_sel_hi:[1,1,0]
	v_pk_fma_f32 v[182:183], v[182:183], v[184:185], s[54:55] op_sel_hi:[1,1,0]
	v_pk_fma_f32 v[158:159], v[158:159], v[160:161], 0.5 op_sel_hi:[1,1,0]
	v_pk_fma_f32 v[164:165], v[164:165], v[166:167], 0.5 op_sel_hi:[1,1,0]
	v_pk_fma_f32 v[170:171], v[170:171], v[172:173], 0.5 op_sel_hi:[1,1,0]
	v_pk_fma_f32 v[180:181], v[180:181], v[182:183], 0.5 op_sel_hi:[1,1,0]
	v_pk_mul_f32 v[76:77], v[76:77], v[158:159]
	v_pk_mul_f32 v[78:79], v[78:79], v[164:165]
	v_pk_mul_f32 v[68:69], v[68:69], v[170:171]
	v_pk_mul_f32 v[70:71], v[70:71], v[180:181]
	v_pk_add_f32 v[158:159], v[80:81], v[82:83]
	v_pk_add_f32 v[160:161], v[72:73], v[74:75]
	v_pk_add_f32 v[162:163], v[76:77], v[78:79]
	v_pk_add_f32 v[164:165], v[68:69], v[70:71]
	v_pk_mul_f32 v[166:167], v[80:81], v[80:81]
	v_pk_mul_f32 v[168:169], v[72:73], v[72:73]
	v_pk_mul_f32 v[170:171], v[76:77], v[76:77]
	v_pk_mul_f32 v[172:173], v[68:69], v[68:69]
	v_pk_fma_f32 v[166:167], v[82:83], v[82:83], v[166:167]
	v_pk_fma_f32 v[168:169], v[74:75], v[74:75], v[168:169]
	v_pk_fma_f32 v[170:171], v[78:79], v[78:79], v[170:171]
	v_pk_fma_f32 v[172:173], v[70:71], v[70:71], v[172:173]
	v_pk_add_f32 v[158:159], v[158:159], v[160:161]
	v_pk_add_f32 v[162:163], v[162:163], v[164:165]
	v_pk_add_f32 v[166:167], v[166:167], v[168:169]
	v_pk_add_f32 v[170:171], v[170:171], v[172:173]
	v_pk_add_f32 v[158:159], v[158:159], v[162:163]
	v_pk_add_f32 v[166:167], v[166:167], v[170:171]
	v_cvt_pk_bf16_f32 v80, v80, v81
	v_cvt_pk_bf16_f32 v81, v82, v83
	v_cvt_pk_bf16_f32 v82, v72, v73
	v_cvt_pk_bf16_f32 v83, v74, v75
	global_store_dwordx4 v207, v[80:83], s[12:13]
	v_cvt_pk_bf16_f32 v76, v76, v77
	v_cvt_pk_bf16_f32 v77, v78, v79
	v_cvt_pk_bf16_f32 v78, v68, v69
	v_cvt_pk_bf16_f32 v79, v70, v71
	global_store_dwordx4 v207, v[76:79], s[12:13] offset:256
	v_add_f32_e32 v72, v158, v159
	v_add_f32_e32 v73, v166, v167
	v_pk_mul_f32 v[64:65], v[64:65], v[244:245] op_sel_hi:[1,0]
	v_pk_mul_f32 v[66:67], v[66:67], v[244:245] op_sel_hi:[1,0]
	v_pk_mul_f32 v[56:57], v[56:57], v[244:245] op_sel_hi:[1,0]
	v_pk_mul_f32 v[58:59], v[58:59], v[244:245] op_sel_hi:[1,0]
	v_pk_mul_f32 v[60:61], v[60:61], v[244:245] op_sel_hi:[1,0]
	v_pk_mul_f32 v[62:63], v[62:63], v[244:245] op_sel_hi:[1,0]
	v_pk_mul_f32 v[52:53], v[52:53], v[244:245] op_sel_hi:[1,0]
	v_pk_mul_f32 v[54:55], v[54:55], v[244:245] op_sel_hi:[1,0]
	v_med3_f32 v158, v64, -4.0, 4.0
	v_med3_f32 v164, v66, -4.0, 4.0
	v_med3_f32 v170, v56, -4.0, 4.0
	v_med3_f32 v180, v58, -4.0, 4.0
	v_med3_f32 v159, v65, -4.0, 4.0
	v_med3_f32 v165, v67, -4.0, 4.0
	v_med3_f32 v171, v57, -4.0, 4.0
	v_med3_f32 v181, v59, -4.0, 4.0
	v_pk_mul_f32 v[160:161], v[158:159], v[158:159]
	v_pk_mul_f32 v[166:167], v[164:165], v[164:165]
	v_pk_mul_f32 v[172:173], v[170:171], v[170:171]
	v_pk_mul_f32 v[182:183], v[180:181], v[180:181]
	v_pk_fma_f32 v[160:161], v[160:161], s[72:73], -1.0 op_sel_hi:[1,0,0]
	v_pk_fma_f32 v[166:167], v[166:167], s[72:73], -1.0 op_sel_hi:[1,0,0]
	v_pk_fma_f32 v[172:173], v[172:173], s[72:73], -1.0 op_sel_hi:[1,0,0]
	v_pk_fma_f32 v[182:183], v[182:183], s[72:73], -1.0 op_sel_hi:[1,0,0]
	v_pk_fma_f32 v[162:163], v[160:161], s[74:75], v[198:199] op_sel_hi:[1,0,0]
	v_pk_fma_f32 v[168:169], v[166:167], s[74:75], v[198:199] op_sel_hi:[1,0,0]
	v_pk_fma_f32 v[178:179], v[172:173], s[74:75], v[198:199] op_sel_hi:[1,0,0]
	v_pk_fma_f32 v[184:185], v[182:183], s[74:75], v[198:199] op_sel_hi:[1,0,0]
	v_pk_fma_f32 v[162:163], v[160:161], v[162:163], s[2:3] op_sel_hi:[1,1,0]
	v_pk_fma_f32 v[168:169], v[166:167], v[168:169], s[2:3] op_sel_hi:[1,1,0]
	v_pk_fma_f32 v[178:179], v[172:173], v[178:179], s[2:3] op_sel_hi:[1,1,0]
	v_pk_fma_f32 v[184:185], v[182:183], v[184:185], s[2:3] op_sel_hi:[1,1,0]
	v_pk_fma_f32 v[162:163], v[160:161], v[162:163], s[28:29] op_sel_hi:[1,1,0]
	v_pk_fma_f32 v[168:169], v[166:167], v[168:169], s[28:29] op_sel_hi:[1,1,0]
	v_pk_fma_f32 v[178:179], v[172:173], v[178:179], s[28:29] op_sel_hi:[1,1,0]
	v_pk_fma_f32 v[184:185], v[182:183], v[184:185], s[28:29] op_sel_hi:[1,1,0]
	v_pk_fma_f32 v[162:163], v[160:161], v[162:163], s[30:31] op_sel_hi:[1,1,0]
	v_pk_fma_f32 v[168:169], v[166:167], v[168:169], s[30:31] op_sel_hi:[1,1,0]
	v_pk_fma_f32 v[178:179], v[172:173], v[178:179], s[30:31] op_sel_hi:[1,1,0]
	v_pk_fma_f32 v[184:185], v[182:183], v[184:185], s[30:31] op_sel_hi:[1,1,0]
	v_pk_fma_f32 v[162:163], v[160:161], v[162:163], s[48:49] op_sel_hi:[1,1,0]
	v_pk_fma_f32 v[168:169], v[166:167], v[168:169], s[48:49] op_sel_hi:[1,1,0]
	v_pk_fma_f32 v[178:179], v[172:173], v[178:179], s[48:49] op_sel_hi:[1,1,0]
	v_pk_fma_f32 v[184:185], v[182:183], v[184:185], s[48:49] op_sel_hi:[1,1,0]
	v_pk_fma_f32 v[162:163], v[160:161], v[162:163], s[50:51] op_sel_hi:[1,1,0]
	v_pk_fma_f32 v[168:169], v[166:167], v[168:169], s[50:51] op_sel_hi:[1,1,0]
	v_pk_fma_f32 v[178:179], v[172:173], v[178:179], s[50:51] op_sel_hi:[1,1,0]
	v_pk_fma_f32 v[184:185], v[182:183], v[184:185], s[50:51] op_sel_hi:[1,1,0]
	v_pk_fma_f32 v[162:163], v[160:161], v[162:163], s[52:53] op_sel_hi:[1,1,0]
	v_pk_fma_f32 v[168:169], v[166:167], v[168:169], s[52:53] op_sel_hi:[1,1,0]
	v_pk_fma_f32 v[178:179], v[172:173], v[178:179], s[52:53] op_sel_hi:[1,1,0]
	v_pk_fma_f32 v[184:185], v[182:183], v[184:185], s[52:53] op_sel_hi:[1,1,0]
	v_pk_fma_f32 v[160:161], v[160:161], v[162:163], s[54:55] op_sel_hi:[1,1,0]
	v_pk_fma_f32 v[166:167], v[166:167], v[168:169], s[54:55] op_sel_hi:[1,1,0]
	v_pk_fma_f32 v[172:173], v[172:173], v[178:179], s[54:55] op_sel_hi:[1,1,0]
	v_pk_fma_f32 v[182:183], v[182:183], v[184:185], s[54:55] op_sel_hi:[1,1,0]
	v_pk_fma_f32 v[158:159], v[158:159], v[160:161], 0.5 op_sel_hi:[1,1,0]
	v_pk_fma_f32 v[164:165], v[164:165], v[166:167], 0.5 op_sel_hi:[1,1,0]
	v_pk_fma_f32 v[170:171], v[170:171], v[172:173], 0.5 op_sel_hi:[1,1,0]
	v_pk_fma_f32 v[180:181], v[180:181], v[182:183], 0.5 op_sel_hi:[1,1,0]
	v_pk_mul_f32 v[64:65], v[64:65], v[158:159]
	v_pk_mul_f32 v[66:67], v[66:67], v[164:165]
	v_pk_mul_f32 v[56:57], v[56:57], v[170:171]
	v_pk_mul_f32 v[58:59], v[58:59], v[180:181]
	v_med3_f32 v158, v60, -4.0, 4.0
	v_med3_f32 v164, v62, -4.0, 4.0
	v_med3_f32 v170, v52, -4.0, 4.0
	v_med3_f32 v180, v54, -4.0, 4.0
	v_med3_f32 v159, v61, -4.0, 4.0
	v_med3_f32 v165, v63, -4.0, 4.0
	v_med3_f32 v171, v53, -4.0, 4.0
	v_med3_f32 v181, v55, -4.0, 4.0
	v_pk_mul_f32 v[160:161], v[158:159], v[158:159]
	v_pk_mul_f32 v[166:167], v[164:165], v[164:165]
	v_pk_mul_f32 v[172:173], v[170:171], v[170:171]
	v_pk_mul_f32 v[182:183], v[180:181], v[180:181]
	v_pk_fma_f32 v[160:161], v[160:161], s[72:73], -1.0 op_sel_hi:[1,0,0]
	v_pk_fma_f32 v[166:167], v[166:167], s[72:73], -1.0 op_sel_hi:[1,0,0]
	v_pk_fma_f32 v[172:173], v[172:173], s[72:73], -1.0 op_sel_hi:[1,0,0]
	v_pk_fma_f32 v[182:183], v[182:183], s[72:73], -1.0 op_sel_hi:[1,0,0]
	v_pk_fma_f32 v[162:163], v[160:161], s[74:75], v[198:199] op_sel_hi:[1,0,0]
	v_pk_fma_f32 v[168:169], v[166:167], s[74:75], v[198:199] op_sel_hi:[1,0,0]
	v_pk_fma_f32 v[178:179], v[172:173], s[74:75], v[198:199] op_sel_hi:[1,0,0]
	v_pk_fma_f32 v[184:185], v[182:183], s[74:75], v[198:199] op_sel_hi:[1,0,0]
	v_pk_fma_f32 v[162:163], v[160:161], v[162:163], s[2:3] op_sel_hi:[1,1,0]
	v_pk_fma_f32 v[168:169], v[166:167], v[168:169], s[2:3] op_sel_hi:[1,1,0]
	v_pk_fma_f32 v[178:179], v[172:173], v[178:179], s[2:3] op_sel_hi:[1,1,0]
	v_pk_fma_f32 v[184:185], v[182:183], v[184:185], s[2:3] op_sel_hi:[1,1,0]
	v_pk_fma_f32 v[162:163], v[160:161], v[162:163], s[28:29] op_sel_hi:[1,1,0]
	v_pk_fma_f32 v[168:169], v[166:167], v[168:169], s[28:29] op_sel_hi:[1,1,0]
	v_pk_fma_f32 v[178:179], v[172:173], v[178:179], s[28:29] op_sel_hi:[1,1,0]
	v_pk_fma_f32 v[184:185], v[182:183], v[184:185], s[28:29] op_sel_hi:[1,1,0]
	v_pk_fma_f32 v[162:163], v[160:161], v[162:163], s[30:31] op_sel_hi:[1,1,0]
	v_pk_fma_f32 v[168:169], v[166:167], v[168:169], s[30:31] op_sel_hi:[1,1,0]
	v_pk_fma_f32 v[178:179], v[172:173], v[178:179], s[30:31] op_sel_hi:[1,1,0]
	v_pk_fma_f32 v[184:185], v[182:183], v[184:185], s[30:31] op_sel_hi:[1,1,0]
	v_pk_fma_f32 v[162:163], v[160:161], v[162:163], s[48:49] op_sel_hi:[1,1,0]
	v_pk_fma_f32 v[168:169], v[166:167], v[168:169], s[48:49] op_sel_hi:[1,1,0]
	v_pk_fma_f32 v[178:179], v[172:173], v[178:179], s[48:49] op_sel_hi:[1,1,0]
	v_pk_fma_f32 v[184:185], v[182:183], v[184:185], s[48:49] op_sel_hi:[1,1,0]
	v_pk_fma_f32 v[162:163], v[160:161], v[162:163], s[50:51] op_sel_hi:[1,1,0]
	v_pk_fma_f32 v[168:169], v[166:167], v[168:169], s[50:51] op_sel_hi:[1,1,0]
	v_pk_fma_f32 v[178:179], v[172:173], v[178:179], s[50:51] op_sel_hi:[1,1,0]
	v_pk_fma_f32 v[184:185], v[182:183], v[184:185], s[50:51] op_sel_hi:[1,1,0]
	v_pk_fma_f32 v[162:163], v[160:161], v[162:163], s[52:53] op_sel_hi:[1,1,0]
	v_pk_fma_f32 v[168:169], v[166:167], v[168:169], s[52:53] op_sel_hi:[1,1,0]
	v_pk_fma_f32 v[178:179], v[172:173], v[178:179], s[52:53] op_sel_hi:[1,1,0]
	v_pk_fma_f32 v[184:185], v[182:183], v[184:185], s[52:53] op_sel_hi:[1,1,0]
	v_pk_fma_f32 v[160:161], v[160:161], v[162:163], s[54:55] op_sel_hi:[1,1,0]
	v_pk_fma_f32 v[166:167], v[166:167], v[168:169], s[54:55] op_sel_hi:[1,1,0]
	v_pk_fma_f32 v[172:173], v[172:173], v[178:179], s[54:55] op_sel_hi:[1,1,0]
	v_pk_fma_f32 v[182:183], v[182:183], v[184:185], s[54:55] op_sel_hi:[1,1,0]
	v_pk_fma_f32 v[158:159], v[158:159], v[160:161], 0.5 op_sel_hi:[1,1,0]
	v_pk_fma_f32 v[164:165], v[164:165], v[166:167], 0.5 op_sel_hi:[1,1,0]
	v_pk_fma_f32 v[170:171], v[170:171], v[172:173], 0.5 op_sel_hi:[1,1,0]
	v_pk_fma_f32 v[180:181], v[180:181], v[182:183], 0.5 op_sel_hi:[1,1,0]
	v_pk_mul_f32 v[60:61], v[60:61], v[158:159]
	v_pk_mul_f32 v[62:63], v[62:63], v[164:165]
	v_pk_mul_f32 v[52:53], v[52:53], v[170:171]
	v_pk_mul_f32 v[54:55], v[54:55], v[180:181]
	v_pk_add_f32 v[158:159], v[64:65], v[66:67]
	v_pk_add_f32 v[160:161], v[56:57], v[58:59]
	v_pk_add_f32 v[162:163], v[60:61], v[62:63]
	v_pk_add_f32 v[164:165], v[52:53], v[54:55]
	v_pk_mul_f32 v[166:167], v[64:65], v[64:65]
	v_pk_mul_f32 v[168:169], v[56:57], v[56:57]
	v_pk_mul_f32 v[170:171], v[60:61], v[60:61]
	v_pk_mul_f32 v[172:173], v[52:53], v[52:53]
	v_pk_fma_f32 v[166:167], v[66:67], v[66:67], v[166:167]
	v_pk_fma_f32 v[168:169], v[58:59], v[58:59], v[168:169]
	v_pk_fma_f32 v[170:171], v[62:63], v[62:63], v[170:171]
	v_pk_fma_f32 v[172:173], v[54:55], v[54:55], v[172:173]
	v_pk_add_f32 v[158:159], v[158:159], v[160:161]
	v_pk_add_f32 v[162:163], v[162:163], v[164:165]
	v_pk_add_f32 v[166:167], v[166:167], v[168:169]
	v_pk_add_f32 v[170:171], v[170:171], v[172:173]
	v_pk_add_f32 v[158:159], v[158:159], v[162:163]
	v_pk_add_f32 v[166:167], v[166:167], v[170:171]
	v_cvt_pk_bf16_f32 v64, v64, v65
	v_cvt_pk_bf16_f32 v65, v66, v67
	v_cvt_pk_bf16_f32 v66, v56, v57
	v_cvt_pk_bf16_f32 v67, v58, v59
	global_store_dwordx4 v209, v[64:67], s[12:13]
	v_cvt_pk_bf16_f32 v60, v60, v61
	v_cvt_pk_bf16_f32 v61, v62, v63
	v_cvt_pk_bf16_f32 v62, v52, v53
	v_cvt_pk_bf16_f32 v63, v54, v55
	global_store_dwordx4 v209, v[60:63], s[12:13] offset:256
	v_add_f32_e32 v56, v158, v159
	v_add_f32_e32 v57, v166, v167
	v_pk_mul_f32 v[48:49], v[48:49], v[246:247] op_sel_hi:[1,0]
	v_pk_mul_f32 v[50:51], v[50:51], v[246:247] op_sel_hi:[1,0]
	v_pk_mul_f32 v[40:41], v[40:41], v[246:247] op_sel_hi:[1,0]
	v_pk_mul_f32 v[42:43], v[42:43], v[246:247] op_sel_hi:[1,0]
	v_pk_mul_f32 v[44:45], v[44:45], v[246:247] op_sel_hi:[1,0]
	v_pk_mul_f32 v[46:47], v[46:47], v[246:247] op_sel_hi:[1,0]
	v_pk_mul_f32 v[36:37], v[36:37], v[246:247] op_sel_hi:[1,0]
	v_pk_mul_f32 v[38:39], v[38:39], v[246:247] op_sel_hi:[1,0]
	v_med3_f32 v158, v48, -4.0, 4.0
	v_med3_f32 v164, v50, -4.0, 4.0
	v_med3_f32 v170, v40, -4.0, 4.0
	v_med3_f32 v180, v42, -4.0, 4.0
	v_med3_f32 v159, v49, -4.0, 4.0
	v_med3_f32 v165, v51, -4.0, 4.0
	v_med3_f32 v171, v41, -4.0, 4.0
	v_med3_f32 v181, v43, -4.0, 4.0
	v_pk_mul_f32 v[160:161], v[158:159], v[158:159]
	v_pk_mul_f32 v[166:167], v[164:165], v[164:165]
	v_pk_mul_f32 v[172:173], v[170:171], v[170:171]
	v_pk_mul_f32 v[182:183], v[180:181], v[180:181]
	v_pk_fma_f32 v[160:161], v[160:161], s[72:73], -1.0 op_sel_hi:[1,0,0]
	v_pk_fma_f32 v[166:167], v[166:167], s[72:73], -1.0 op_sel_hi:[1,0,0]
	v_pk_fma_f32 v[172:173], v[172:173], s[72:73], -1.0 op_sel_hi:[1,0,0]
	v_pk_fma_f32 v[182:183], v[182:183], s[72:73], -1.0 op_sel_hi:[1,0,0]
	v_pk_fma_f32 v[162:163], v[160:161], s[74:75], v[198:199] op_sel_hi:[1,0,0]
	v_pk_fma_f32 v[168:169], v[166:167], s[74:75], v[198:199] op_sel_hi:[1,0,0]
	v_pk_fma_f32 v[178:179], v[172:173], s[74:75], v[198:199] op_sel_hi:[1,0,0]
	v_pk_fma_f32 v[184:185], v[182:183], s[74:75], v[198:199] op_sel_hi:[1,0,0]
	v_pk_fma_f32 v[162:163], v[160:161], v[162:163], s[2:3] op_sel_hi:[1,1,0]
	v_pk_fma_f32 v[168:169], v[166:167], v[168:169], s[2:3] op_sel_hi:[1,1,0]
	v_pk_fma_f32 v[178:179], v[172:173], v[178:179], s[2:3] op_sel_hi:[1,1,0]
	v_pk_fma_f32 v[184:185], v[182:183], v[184:185], s[2:3] op_sel_hi:[1,1,0]
	v_pk_fma_f32 v[162:163], v[160:161], v[162:163], s[28:29] op_sel_hi:[1,1,0]
	v_pk_fma_f32 v[168:169], v[166:167], v[168:169], s[28:29] op_sel_hi:[1,1,0]
	v_pk_fma_f32 v[178:179], v[172:173], v[178:179], s[28:29] op_sel_hi:[1,1,0]
	v_pk_fma_f32 v[184:185], v[182:183], v[184:185], s[28:29] op_sel_hi:[1,1,0]
	v_pk_fma_f32 v[162:163], v[160:161], v[162:163], s[30:31] op_sel_hi:[1,1,0]
	v_pk_fma_f32 v[168:169], v[166:167], v[168:169], s[30:31] op_sel_hi:[1,1,0]
	v_pk_fma_f32 v[178:179], v[172:173], v[178:179], s[30:31] op_sel_hi:[1,1,0]
	v_pk_fma_f32 v[184:185], v[182:183], v[184:185], s[30:31] op_sel_hi:[1,1,0]
	v_pk_fma_f32 v[162:163], v[160:161], v[162:163], s[48:49] op_sel_hi:[1,1,0]
	v_pk_fma_f32 v[168:169], v[166:167], v[168:169], s[48:49] op_sel_hi:[1,1,0]
	v_pk_fma_f32 v[178:179], v[172:173], v[178:179], s[48:49] op_sel_hi:[1,1,0]
	v_pk_fma_f32 v[184:185], v[182:183], v[184:185], s[48:49] op_sel_hi:[1,1,0]
	v_pk_fma_f32 v[162:163], v[160:161], v[162:163], s[50:51] op_sel_hi:[1,1,0]
	v_pk_fma_f32 v[168:169], v[166:167], v[168:169], s[50:51] op_sel_hi:[1,1,0]
	v_pk_fma_f32 v[178:179], v[172:173], v[178:179], s[50:51] op_sel_hi:[1,1,0]
	v_pk_fma_f32 v[184:185], v[182:183], v[184:185], s[50:51] op_sel_hi:[1,1,0]
	v_pk_fma_f32 v[162:163], v[160:161], v[162:163], s[52:53] op_sel_hi:[1,1,0]
	v_pk_fma_f32 v[168:169], v[166:167], v[168:169], s[52:53] op_sel_hi:[1,1,0]
	v_pk_fma_f32 v[178:179], v[172:173], v[178:179], s[52:53] op_sel_hi:[1,1,0]
	v_pk_fma_f32 v[184:185], v[182:183], v[184:185], s[52:53] op_sel_hi:[1,1,0]
	v_pk_fma_f32 v[160:161], v[160:161], v[162:163], s[54:55] op_sel_hi:[1,1,0]
	v_pk_fma_f32 v[166:167], v[166:167], v[168:169], s[54:55] op_sel_hi:[1,1,0]
	v_pk_fma_f32 v[172:173], v[172:173], v[178:179], s[54:55] op_sel_hi:[1,1,0]
	v_pk_fma_f32 v[182:183], v[182:183], v[184:185], s[54:55] op_sel_hi:[1,1,0]
	v_pk_fma_f32 v[158:159], v[158:159], v[160:161], 0.5 op_sel_hi:[1,1,0]
	v_pk_fma_f32 v[164:165], v[164:165], v[166:167], 0.5 op_sel_hi:[1,1,0]
	v_pk_fma_f32 v[170:171], v[170:171], v[172:173], 0.5 op_sel_hi:[1,1,0]
	v_pk_fma_f32 v[180:181], v[180:181], v[182:183], 0.5 op_sel_hi:[1,1,0]
	v_pk_mul_f32 v[48:49], v[48:49], v[158:159]
	v_pk_mul_f32 v[50:51], v[50:51], v[164:165]
	v_pk_mul_f32 v[40:41], v[40:41], v[170:171]
	v_pk_mul_f32 v[42:43], v[42:43], v[180:181]
	v_med3_f32 v158, v44, -4.0, 4.0
	v_med3_f32 v164, v46, -4.0, 4.0
	v_med3_f32 v170, v36, -4.0, 4.0
	v_med3_f32 v180, v38, -4.0, 4.0
	v_med3_f32 v159, v45, -4.0, 4.0
	v_med3_f32 v165, v47, -4.0, 4.0
	v_med3_f32 v171, v37, -4.0, 4.0
	v_med3_f32 v181, v39, -4.0, 4.0
	v_pk_mul_f32 v[160:161], v[158:159], v[158:159]
	v_pk_mul_f32 v[166:167], v[164:165], v[164:165]
	v_pk_mul_f32 v[172:173], v[170:171], v[170:171]
	v_pk_mul_f32 v[182:183], v[180:181], v[180:181]
	v_pk_fma_f32 v[160:161], v[160:161], s[72:73], -1.0 op_sel_hi:[1,0,0]
	v_pk_fma_f32 v[166:167], v[166:167], s[72:73], -1.0 op_sel_hi:[1,0,0]
	v_pk_fma_f32 v[172:173], v[172:173], s[72:73], -1.0 op_sel_hi:[1,0,0]
	v_pk_fma_f32 v[182:183], v[182:183], s[72:73], -1.0 op_sel_hi:[1,0,0]
	v_pk_fma_f32 v[162:163], v[160:161], s[74:75], v[198:199] op_sel_hi:[1,0,0]
	v_pk_fma_f32 v[168:169], v[166:167], s[74:75], v[198:199] op_sel_hi:[1,0,0]
	v_pk_fma_f32 v[178:179], v[172:173], s[74:75], v[198:199] op_sel_hi:[1,0,0]
	v_pk_fma_f32 v[184:185], v[182:183], s[74:75], v[198:199] op_sel_hi:[1,0,0]
	v_pk_fma_f32 v[162:163], v[160:161], v[162:163], s[2:3] op_sel_hi:[1,1,0]
	v_pk_fma_f32 v[168:169], v[166:167], v[168:169], s[2:3] op_sel_hi:[1,1,0]
	v_pk_fma_f32 v[178:179], v[172:173], v[178:179], s[2:3] op_sel_hi:[1,1,0]
	v_pk_fma_f32 v[184:185], v[182:183], v[184:185], s[2:3] op_sel_hi:[1,1,0]
	v_pk_fma_f32 v[162:163], v[160:161], v[162:163], s[28:29] op_sel_hi:[1,1,0]
	v_pk_fma_f32 v[168:169], v[166:167], v[168:169], s[28:29] op_sel_hi:[1,1,0]
	v_pk_fma_f32 v[178:179], v[172:173], v[178:179], s[28:29] op_sel_hi:[1,1,0]
	v_pk_fma_f32 v[184:185], v[182:183], v[184:185], s[28:29] op_sel_hi:[1,1,0]
	v_pk_fma_f32 v[162:163], v[160:161], v[162:163], s[30:31] op_sel_hi:[1,1,0]
	v_pk_fma_f32 v[168:169], v[166:167], v[168:169], s[30:31] op_sel_hi:[1,1,0]
	v_pk_fma_f32 v[178:179], v[172:173], v[178:179], s[30:31] op_sel_hi:[1,1,0]
	v_pk_fma_f32 v[184:185], v[182:183], v[184:185], s[30:31] op_sel_hi:[1,1,0]
	v_pk_fma_f32 v[162:163], v[160:161], v[162:163], s[48:49] op_sel_hi:[1,1,0]
	v_pk_fma_f32 v[168:169], v[166:167], v[168:169], s[48:49] op_sel_hi:[1,1,0]
	v_pk_fma_f32 v[178:179], v[172:173], v[178:179], s[48:49] op_sel_hi:[1,1,0]
	v_pk_fma_f32 v[184:185], v[182:183], v[184:185], s[48:49] op_sel_hi:[1,1,0]
	v_pk_fma_f32 v[162:163], v[160:161], v[162:163], s[50:51] op_sel_hi:[1,1,0]
	v_pk_fma_f32 v[168:169], v[166:167], v[168:169], s[50:51] op_sel_hi:[1,1,0]
	v_pk_fma_f32 v[178:179], v[172:173], v[178:179], s[50:51] op_sel_hi:[1,1,0]
	v_pk_fma_f32 v[184:185], v[182:183], v[184:185], s[50:51] op_sel_hi:[1,1,0]
	v_pk_fma_f32 v[162:163], v[160:161], v[162:163], s[52:53] op_sel_hi:[1,1,0]
	v_pk_fma_f32 v[168:169], v[166:167], v[168:169], s[52:53] op_sel_hi:[1,1,0]
	v_pk_fma_f32 v[178:179], v[172:173], v[178:179], s[52:53] op_sel_hi:[1,1,0]
	v_pk_fma_f32 v[184:185], v[182:183], v[184:185], s[52:53] op_sel_hi:[1,1,0]
	v_pk_fma_f32 v[160:161], v[160:161], v[162:163], s[54:55] op_sel_hi:[1,1,0]
	v_pk_fma_f32 v[166:167], v[166:167], v[168:169], s[54:55] op_sel_hi:[1,1,0]
	v_pk_fma_f32 v[172:173], v[172:173], v[178:179], s[54:55] op_sel_hi:[1,1,0]
	v_pk_fma_f32 v[182:183], v[182:183], v[184:185], s[54:55] op_sel_hi:[1,1,0]
	v_pk_fma_f32 v[158:159], v[158:159], v[160:161], 0.5 op_sel_hi:[1,1,0]
	v_pk_fma_f32 v[164:165], v[164:165], v[166:167], 0.5 op_sel_hi:[1,1,0]
	v_pk_fma_f32 v[170:171], v[170:171], v[172:173], 0.5 op_sel_hi:[1,1,0]
	v_pk_fma_f32 v[180:181], v[180:181], v[182:183], 0.5 op_sel_hi:[1,1,0]
	v_pk_mul_f32 v[44:45], v[44:45], v[158:159]
	v_pk_mul_f32 v[46:47], v[46:47], v[164:165]
	v_pk_mul_f32 v[36:37], v[36:37], v[170:171]
	v_pk_mul_f32 v[38:39], v[38:39], v[180:181]
	v_pk_add_f32 v[158:159], v[48:49], v[50:51]
	v_pk_add_f32 v[160:161], v[40:41], v[42:43]
	v_pk_add_f32 v[162:163], v[44:45], v[46:47]
	v_pk_add_f32 v[164:165], v[36:37], v[38:39]
	v_pk_mul_f32 v[166:167], v[48:49], v[48:49]
	v_pk_mul_f32 v[168:169], v[40:41], v[40:41]
	v_pk_mul_f32 v[170:171], v[44:45], v[44:45]
	v_pk_mul_f32 v[172:173], v[36:37], v[36:37]
	v_pk_fma_f32 v[166:167], v[50:51], v[50:51], v[166:167]
	v_pk_fma_f32 v[168:169], v[42:43], v[42:43], v[168:169]
	v_pk_fma_f32 v[170:171], v[46:47], v[46:47], v[170:171]
	v_pk_fma_f32 v[172:173], v[38:39], v[38:39], v[172:173]
	v_pk_add_f32 v[158:159], v[158:159], v[160:161]
	v_pk_add_f32 v[162:163], v[162:163], v[164:165]
	v_pk_add_f32 v[166:167], v[166:167], v[168:169]
	v_pk_add_f32 v[170:171], v[170:171], v[172:173]
	v_pk_add_f32 v[158:159], v[158:159], v[162:163]
	v_pk_add_f32 v[166:167], v[166:167], v[170:171]
	v_cvt_pk_bf16_f32 v48, v48, v49
	v_cvt_pk_bf16_f32 v49, v50, v51
	v_cvt_pk_bf16_f32 v50, v40, v41
	v_cvt_pk_bf16_f32 v51, v42, v43
	global_store_dwordx4 v211, v[48:51], s[12:13]
	v_cvt_pk_bf16_f32 v44, v44, v45
	v_cvt_pk_bf16_f32 v45, v46, v47
	v_cvt_pk_bf16_f32 v46, v36, v37
	v_cvt_pk_bf16_f32 v47, v38, v39
	global_store_dwordx4 v211, v[44:47], s[12:13] offset:256
	v_add_f32_e32 v40, v158, v159
	v_add_f32_e32 v41, v166, v167
	v_pk_mul_f32 v[32:33], v[32:33], v[248:249] op_sel_hi:[1,0]
	v_pk_mul_f32 v[34:35], v[34:35], v[248:249] op_sel_hi:[1,0]
	v_pk_mul_f32 v[24:25], v[24:25], v[248:249] op_sel_hi:[1,0]
	v_pk_mul_f32 v[26:27], v[26:27], v[248:249] op_sel_hi:[1,0]
	v_pk_mul_f32 v[28:29], v[28:29], v[248:249] op_sel_hi:[1,0]
	v_pk_mul_f32 v[30:31], v[30:31], v[248:249] op_sel_hi:[1,0]
	v_pk_mul_f32 v[20:21], v[20:21], v[248:249] op_sel_hi:[1,0]
	v_pk_mul_f32 v[22:23], v[22:23], v[248:249] op_sel_hi:[1,0]
	v_med3_f32 v158, v32, -4.0, 4.0
	v_med3_f32 v164, v34, -4.0, 4.0
	v_med3_f32 v170, v24, -4.0, 4.0
	v_med3_f32 v180, v26, -4.0, 4.0
	v_med3_f32 v159, v33, -4.0, 4.0
	v_med3_f32 v165, v35, -4.0, 4.0
	v_med3_f32 v171, v25, -4.0, 4.0
	v_med3_f32 v181, v27, -4.0, 4.0
	v_pk_mul_f32 v[160:161], v[158:159], v[158:159]
	v_pk_mul_f32 v[166:167], v[164:165], v[164:165]
	v_pk_mul_f32 v[172:173], v[170:171], v[170:171]
	v_pk_mul_f32 v[182:183], v[180:181], v[180:181]
	v_pk_fma_f32 v[160:161], v[160:161], s[72:73], -1.0 op_sel_hi:[1,0,0]
	v_pk_fma_f32 v[166:167], v[166:167], s[72:73], -1.0 op_sel_hi:[1,0,0]
	v_pk_fma_f32 v[172:173], v[172:173], s[72:73], -1.0 op_sel_hi:[1,0,0]
	v_pk_fma_f32 v[182:183], v[182:183], s[72:73], -1.0 op_sel_hi:[1,0,0]
	v_pk_fma_f32 v[162:163], v[160:161], s[74:75], v[198:199] op_sel_hi:[1,0,0]
	v_pk_fma_f32 v[168:169], v[166:167], s[74:75], v[198:199] op_sel_hi:[1,0,0]
	v_pk_fma_f32 v[178:179], v[172:173], s[74:75], v[198:199] op_sel_hi:[1,0,0]
	v_pk_fma_f32 v[184:185], v[182:183], s[74:75], v[198:199] op_sel_hi:[1,0,0]
	v_pk_fma_f32 v[162:163], v[160:161], v[162:163], s[2:3] op_sel_hi:[1,1,0]
	v_pk_fma_f32 v[168:169], v[166:167], v[168:169], s[2:3] op_sel_hi:[1,1,0]
	v_pk_fma_f32 v[178:179], v[172:173], v[178:179], s[2:3] op_sel_hi:[1,1,0]
	v_pk_fma_f32 v[184:185], v[182:183], v[184:185], s[2:3] op_sel_hi:[1,1,0]
	v_pk_fma_f32 v[162:163], v[160:161], v[162:163], s[28:29] op_sel_hi:[1,1,0]
	v_pk_fma_f32 v[168:169], v[166:167], v[168:169], s[28:29] op_sel_hi:[1,1,0]
	v_pk_fma_f32 v[178:179], v[172:173], v[178:179], s[28:29] op_sel_hi:[1,1,0]
	v_pk_fma_f32 v[184:185], v[182:183], v[184:185], s[28:29] op_sel_hi:[1,1,0]
	v_pk_fma_f32 v[162:163], v[160:161], v[162:163], s[30:31] op_sel_hi:[1,1,0]
	v_pk_fma_f32 v[168:169], v[166:167], v[168:169], s[30:31] op_sel_hi:[1,1,0]
	v_pk_fma_f32 v[178:179], v[172:173], v[178:179], s[30:31] op_sel_hi:[1,1,0]
	v_pk_fma_f32 v[184:185], v[182:183], v[184:185], s[30:31] op_sel_hi:[1,1,0]
	v_pk_fma_f32 v[162:163], v[160:161], v[162:163], s[48:49] op_sel_hi:[1,1,0]
	v_pk_fma_f32 v[168:169], v[166:167], v[168:169], s[48:49] op_sel_hi:[1,1,0]
	v_pk_fma_f32 v[178:179], v[172:173], v[178:179], s[48:49] op_sel_hi:[1,1,0]
	v_pk_fma_f32 v[184:185], v[182:183], v[184:185], s[48:49] op_sel_hi:[1,1,0]
	v_pk_fma_f32 v[162:163], v[160:161], v[162:163], s[50:51] op_sel_hi:[1,1,0]
	v_pk_fma_f32 v[168:169], v[166:167], v[168:169], s[50:51] op_sel_hi:[1,1,0]
	v_pk_fma_f32 v[178:179], v[172:173], v[178:179], s[50:51] op_sel_hi:[1,1,0]
	v_pk_fma_f32 v[184:185], v[182:183], v[184:185], s[50:51] op_sel_hi:[1,1,0]
	v_pk_fma_f32 v[162:163], v[160:161], v[162:163], s[52:53] op_sel_hi:[1,1,0]
	v_pk_fma_f32 v[168:169], v[166:167], v[168:169], s[52:53] op_sel_hi:[1,1,0]
	v_pk_fma_f32 v[178:179], v[172:173], v[178:179], s[52:53] op_sel_hi:[1,1,0]
	v_pk_fma_f32 v[184:185], v[182:183], v[184:185], s[52:53] op_sel_hi:[1,1,0]
	v_pk_fma_f32 v[160:161], v[160:161], v[162:163], s[54:55] op_sel_hi:[1,1,0]
	v_pk_fma_f32 v[166:167], v[166:167], v[168:169], s[54:55] op_sel_hi:[1,1,0]
	v_pk_fma_f32 v[172:173], v[172:173], v[178:179], s[54:55] op_sel_hi:[1,1,0]
	v_pk_fma_f32 v[182:183], v[182:183], v[184:185], s[54:55] op_sel_hi:[1,1,0]
	v_pk_fma_f32 v[158:159], v[158:159], v[160:161], 0.5 op_sel_hi:[1,1,0]
	v_pk_fma_f32 v[164:165], v[164:165], v[166:167], 0.5 op_sel_hi:[1,1,0]
	v_pk_fma_f32 v[170:171], v[170:171], v[172:173], 0.5 op_sel_hi:[1,1,0]
	v_pk_fma_f32 v[180:181], v[180:181], v[182:183], 0.5 op_sel_hi:[1,1,0]
	v_pk_mul_f32 v[32:33], v[32:33], v[158:159]
	v_pk_mul_f32 v[34:35], v[34:35], v[164:165]
	v_pk_mul_f32 v[24:25], v[24:25], v[170:171]
	v_pk_mul_f32 v[26:27], v[26:27], v[180:181]
	v_med3_f32 v158, v28, -4.0, 4.0
	v_med3_f32 v164, v30, -4.0, 4.0
	v_med3_f32 v170, v20, -4.0, 4.0
	v_med3_f32 v180, v22, -4.0, 4.0
	v_med3_f32 v159, v29, -4.0, 4.0
	v_med3_f32 v165, v31, -4.0, 4.0
	v_med3_f32 v171, v21, -4.0, 4.0
	v_med3_f32 v181, v23, -4.0, 4.0
	v_pk_mul_f32 v[160:161], v[158:159], v[158:159]
	v_pk_mul_f32 v[166:167], v[164:165], v[164:165]
	v_pk_mul_f32 v[172:173], v[170:171], v[170:171]
	v_pk_mul_f32 v[182:183], v[180:181], v[180:181]
	v_pk_fma_f32 v[160:161], v[160:161], s[72:73], -1.0 op_sel_hi:[1,0,0]
	v_pk_fma_f32 v[166:167], v[166:167], s[72:73], -1.0 op_sel_hi:[1,0,0]
	v_pk_fma_f32 v[172:173], v[172:173], s[72:73], -1.0 op_sel_hi:[1,0,0]
	v_pk_fma_f32 v[182:183], v[182:183], s[72:73], -1.0 op_sel_hi:[1,0,0]
	v_pk_fma_f32 v[162:163], v[160:161], s[74:75], v[198:199] op_sel_hi:[1,0,0]
	v_pk_fma_f32 v[168:169], v[166:167], s[74:75], v[198:199] op_sel_hi:[1,0,0]
	v_pk_fma_f32 v[178:179], v[172:173], s[74:75], v[198:199] op_sel_hi:[1,0,0]
	v_pk_fma_f32 v[184:185], v[182:183], s[74:75], v[198:199] op_sel_hi:[1,0,0]
	v_pk_fma_f32 v[162:163], v[160:161], v[162:163], s[2:3] op_sel_hi:[1,1,0]
	v_pk_fma_f32 v[168:169], v[166:167], v[168:169], s[2:3] op_sel_hi:[1,1,0]
	v_pk_fma_f32 v[178:179], v[172:173], v[178:179], s[2:3] op_sel_hi:[1,1,0]
	v_pk_fma_f32 v[184:185], v[182:183], v[184:185], s[2:3] op_sel_hi:[1,1,0]
	v_pk_fma_f32 v[162:163], v[160:161], v[162:163], s[28:29] op_sel_hi:[1,1,0]
	v_pk_fma_f32 v[168:169], v[166:167], v[168:169], s[28:29] op_sel_hi:[1,1,0]
	v_pk_fma_f32 v[178:179], v[172:173], v[178:179], s[28:29] op_sel_hi:[1,1,0]
	v_pk_fma_f32 v[184:185], v[182:183], v[184:185], s[28:29] op_sel_hi:[1,1,0]
	v_pk_fma_f32 v[162:163], v[160:161], v[162:163], s[30:31] op_sel_hi:[1,1,0]
	v_pk_fma_f32 v[168:169], v[166:167], v[168:169], s[30:31] op_sel_hi:[1,1,0]
	v_pk_fma_f32 v[178:179], v[172:173], v[178:179], s[30:31] op_sel_hi:[1,1,0]
	v_pk_fma_f32 v[184:185], v[182:183], v[184:185], s[30:31] op_sel_hi:[1,1,0]
	v_pk_fma_f32 v[162:163], v[160:161], v[162:163], s[48:49] op_sel_hi:[1,1,0]
	v_pk_fma_f32 v[168:169], v[166:167], v[168:169], s[48:49] op_sel_hi:[1,1,0]
	v_pk_fma_f32 v[178:179], v[172:173], v[178:179], s[48:49] op_sel_hi:[1,1,0]
	v_pk_fma_f32 v[184:185], v[182:183], v[184:185], s[48:49] op_sel_hi:[1,1,0]
	v_pk_fma_f32 v[162:163], v[160:161], v[162:163], s[50:51] op_sel_hi:[1,1,0]
	v_pk_fma_f32 v[168:169], v[166:167], v[168:169], s[50:51] op_sel_hi:[1,1,0]
	v_pk_fma_f32 v[178:179], v[172:173], v[178:179], s[50:51] op_sel_hi:[1,1,0]
	v_pk_fma_f32 v[184:185], v[182:183], v[184:185], s[50:51] op_sel_hi:[1,1,0]
	v_pk_fma_f32 v[162:163], v[160:161], v[162:163], s[52:53] op_sel_hi:[1,1,0]
	v_pk_fma_f32 v[168:169], v[166:167], v[168:169], s[52:53] op_sel_hi:[1,1,0]
	v_pk_fma_f32 v[178:179], v[172:173], v[178:179], s[52:53] op_sel_hi:[1,1,0]
	v_pk_fma_f32 v[184:185], v[182:183], v[184:185], s[52:53] op_sel_hi:[1,1,0]
	v_pk_fma_f32 v[160:161], v[160:161], v[162:163], s[54:55] op_sel_hi:[1,1,0]
	v_pk_fma_f32 v[166:167], v[166:167], v[168:169], s[54:55] op_sel_hi:[1,1,0]
	v_pk_fma_f32 v[172:173], v[172:173], v[178:179], s[54:55] op_sel_hi:[1,1,0]
	v_pk_fma_f32 v[182:183], v[182:183], v[184:185], s[54:55] op_sel_hi:[1,1,0]
	v_pk_fma_f32 v[158:159], v[158:159], v[160:161], 0.5 op_sel_hi:[1,1,0]
	v_pk_fma_f32 v[164:165], v[164:165], v[166:167], 0.5 op_sel_hi:[1,1,0]
	v_pk_fma_f32 v[170:171], v[170:171], v[172:173], 0.5 op_sel_hi:[1,1,0]
	v_pk_fma_f32 v[180:181], v[180:181], v[182:183], 0.5 op_sel_hi:[1,1,0]
	v_pk_mul_f32 v[28:29], v[28:29], v[158:159]
	v_pk_mul_f32 v[30:31], v[30:31], v[164:165]
	v_pk_mul_f32 v[20:21], v[20:21], v[170:171]
	v_pk_mul_f32 v[22:23], v[22:23], v[180:181]
	v_pk_add_f32 v[158:159], v[32:33], v[34:35]
	v_pk_add_f32 v[160:161], v[24:25], v[26:27]
	v_pk_add_f32 v[162:163], v[28:29], v[30:31]
	v_pk_add_f32 v[164:165], v[20:21], v[22:23]
	v_pk_mul_f32 v[166:167], v[32:33], v[32:33]
	v_pk_mul_f32 v[168:169], v[24:25], v[24:25]
	v_pk_mul_f32 v[170:171], v[28:29], v[28:29]
	v_pk_mul_f32 v[172:173], v[20:21], v[20:21]
	v_pk_fma_f32 v[166:167], v[34:35], v[34:35], v[166:167]
	v_pk_fma_f32 v[168:169], v[26:27], v[26:27], v[168:169]
	v_pk_fma_f32 v[170:171], v[30:31], v[30:31], v[170:171]
	v_pk_fma_f32 v[172:173], v[22:23], v[22:23], v[172:173]
	v_pk_add_f32 v[158:159], v[158:159], v[160:161]
	v_pk_add_f32 v[162:163], v[162:163], v[164:165]
	v_pk_add_f32 v[166:167], v[166:167], v[168:169]
	v_pk_add_f32 v[170:171], v[170:171], v[172:173]
	v_pk_add_f32 v[158:159], v[158:159], v[162:163]
	v_pk_add_f32 v[166:167], v[166:167], v[170:171]
	v_cvt_pk_bf16_f32 v32, v32, v33
	v_cvt_pk_bf16_f32 v33, v34, v35
	v_cvt_pk_bf16_f32 v34, v24, v25
	v_cvt_pk_bf16_f32 v35, v26, v27
	global_store_dwordx4 v213, v[32:35], s[12:13]
	v_cvt_pk_bf16_f32 v28, v28, v29
	v_cvt_pk_bf16_f32 v29, v30, v31
	v_cvt_pk_bf16_f32 v30, v20, v21
	v_cvt_pk_bf16_f32 v31, v22, v23
	global_store_dwordx4 v213, v[28:31], s[12:13] offset:256
	v_add_f32_e32 v24, v158, v159
	v_add_f32_e32 v25, v166, v167
	v_pk_mul_f32 v[16:17], v[16:17], v[250:251] op_sel_hi:[1,0]
	v_pk_mul_f32 v[18:19], v[18:19], v[250:251] op_sel_hi:[1,0]
	v_pk_mul_f32 v[8:9], v[8:9], v[250:251] op_sel_hi:[1,0]
	v_pk_mul_f32 v[10:11], v[10:11], v[250:251] op_sel_hi:[1,0]
	v_pk_mul_f32 v[12:13], v[12:13], v[250:251] op_sel_hi:[1,0]
	v_pk_mul_f32 v[14:15], v[14:15], v[250:251] op_sel_hi:[1,0]
	v_pk_mul_f32 v[4:5], v[4:5], v[250:251] op_sel_hi:[1,0]
	v_pk_mul_f32 v[6:7], v[6:7], v[250:251] op_sel_hi:[1,0]
	v_med3_f32 v158, v16, -4.0, 4.0
	v_med3_f32 v164, v18, -4.0, 4.0
	v_med3_f32 v170, v8, -4.0, 4.0
	v_med3_f32 v180, v10, -4.0, 4.0
	v_med3_f32 v159, v17, -4.0, 4.0
	v_med3_f32 v165, v19, -4.0, 4.0
	v_med3_f32 v171, v9, -4.0, 4.0
	v_med3_f32 v181, v11, -4.0, 4.0
	v_pk_mul_f32 v[160:161], v[158:159], v[158:159]
	v_pk_mul_f32 v[166:167], v[164:165], v[164:165]
	v_pk_mul_f32 v[172:173], v[170:171], v[170:171]
	v_pk_mul_f32 v[182:183], v[180:181], v[180:181]
	v_pk_fma_f32 v[160:161], v[160:161], s[72:73], -1.0 op_sel_hi:[1,0,0]
	v_pk_fma_f32 v[166:167], v[166:167], s[72:73], -1.0 op_sel_hi:[1,0,0]
	v_pk_fma_f32 v[172:173], v[172:173], s[72:73], -1.0 op_sel_hi:[1,0,0]
	v_pk_fma_f32 v[182:183], v[182:183], s[72:73], -1.0 op_sel_hi:[1,0,0]
	v_pk_fma_f32 v[162:163], v[160:161], s[74:75], v[198:199] op_sel_hi:[1,0,0]
	v_pk_fma_f32 v[168:169], v[166:167], s[74:75], v[198:199] op_sel_hi:[1,0,0]
	v_pk_fma_f32 v[178:179], v[172:173], s[74:75], v[198:199] op_sel_hi:[1,0,0]
	v_pk_fma_f32 v[184:185], v[182:183], s[74:75], v[198:199] op_sel_hi:[1,0,0]
	v_pk_fma_f32 v[162:163], v[160:161], v[162:163], s[2:3] op_sel_hi:[1,1,0]
	v_pk_fma_f32 v[168:169], v[166:167], v[168:169], s[2:3] op_sel_hi:[1,1,0]
	v_pk_fma_f32 v[178:179], v[172:173], v[178:179], s[2:3] op_sel_hi:[1,1,0]
	v_pk_fma_f32 v[184:185], v[182:183], v[184:185], s[2:3] op_sel_hi:[1,1,0]
	v_pk_fma_f32 v[162:163], v[160:161], v[162:163], s[28:29] op_sel_hi:[1,1,0]
	v_pk_fma_f32 v[168:169], v[166:167], v[168:169], s[28:29] op_sel_hi:[1,1,0]
	v_pk_fma_f32 v[178:179], v[172:173], v[178:179], s[28:29] op_sel_hi:[1,1,0]
	v_pk_fma_f32 v[184:185], v[182:183], v[184:185], s[28:29] op_sel_hi:[1,1,0]
	v_pk_fma_f32 v[162:163], v[160:161], v[162:163], s[30:31] op_sel_hi:[1,1,0]
	v_pk_fma_f32 v[168:169], v[166:167], v[168:169], s[30:31] op_sel_hi:[1,1,0]
	v_pk_fma_f32 v[178:179], v[172:173], v[178:179], s[30:31] op_sel_hi:[1,1,0]
	v_pk_fma_f32 v[184:185], v[182:183], v[184:185], s[30:31] op_sel_hi:[1,1,0]
	v_pk_fma_f32 v[162:163], v[160:161], v[162:163], s[48:49] op_sel_hi:[1,1,0]
	v_pk_fma_f32 v[168:169], v[166:167], v[168:169], s[48:49] op_sel_hi:[1,1,0]
	v_pk_fma_f32 v[178:179], v[172:173], v[178:179], s[48:49] op_sel_hi:[1,1,0]
	v_pk_fma_f32 v[184:185], v[182:183], v[184:185], s[48:49] op_sel_hi:[1,1,0]
	v_pk_fma_f32 v[162:163], v[160:161], v[162:163], s[50:51] op_sel_hi:[1,1,0]
	v_pk_fma_f32 v[168:169], v[166:167], v[168:169], s[50:51] op_sel_hi:[1,1,0]
	v_pk_fma_f32 v[178:179], v[172:173], v[178:179], s[50:51] op_sel_hi:[1,1,0]
	v_pk_fma_f32 v[184:185], v[182:183], v[184:185], s[50:51] op_sel_hi:[1,1,0]
	v_pk_fma_f32 v[162:163], v[160:161], v[162:163], s[52:53] op_sel_hi:[1,1,0]
	v_pk_fma_f32 v[168:169], v[166:167], v[168:169], s[52:53] op_sel_hi:[1,1,0]
	v_pk_fma_f32 v[178:179], v[172:173], v[178:179], s[52:53] op_sel_hi:[1,1,0]
	v_pk_fma_f32 v[184:185], v[182:183], v[184:185], s[52:53] op_sel_hi:[1,1,0]
	v_pk_fma_f32 v[160:161], v[160:161], v[162:163], s[54:55] op_sel_hi:[1,1,0]
	v_pk_fma_f32 v[166:167], v[166:167], v[168:169], s[54:55] op_sel_hi:[1,1,0]
	v_pk_fma_f32 v[172:173], v[172:173], v[178:179], s[54:55] op_sel_hi:[1,1,0]
	v_pk_fma_f32 v[182:183], v[182:183], v[184:185], s[54:55] op_sel_hi:[1,1,0]
	v_pk_fma_f32 v[158:159], v[158:159], v[160:161], 0.5 op_sel_hi:[1,1,0]
	v_pk_fma_f32 v[164:165], v[164:165], v[166:167], 0.5 op_sel_hi:[1,1,0]
	v_pk_fma_f32 v[170:171], v[170:171], v[172:173], 0.5 op_sel_hi:[1,1,0]
	v_pk_fma_f32 v[180:181], v[180:181], v[182:183], 0.5 op_sel_hi:[1,1,0]
	v_pk_mul_f32 v[16:17], v[16:17], v[158:159]
	v_pk_mul_f32 v[18:19], v[18:19], v[164:165]
	v_pk_mul_f32 v[8:9], v[8:9], v[170:171]
	v_pk_mul_f32 v[10:11], v[10:11], v[180:181]
	v_med3_f32 v158, v12, -4.0, 4.0
	v_med3_f32 v164, v14, -4.0, 4.0
	v_med3_f32 v170, v4, -4.0, 4.0
	v_med3_f32 v180, v6, -4.0, 4.0
	v_med3_f32 v159, v13, -4.0, 4.0
	v_med3_f32 v165, v15, -4.0, 4.0
	v_med3_f32 v171, v5, -4.0, 4.0
	v_med3_f32 v181, v7, -4.0, 4.0
	v_pk_mul_f32 v[160:161], v[158:159], v[158:159]
	v_pk_mul_f32 v[166:167], v[164:165], v[164:165]
	v_pk_mul_f32 v[172:173], v[170:171], v[170:171]
	v_pk_mul_f32 v[182:183], v[180:181], v[180:181]
	v_pk_fma_f32 v[160:161], v[160:161], s[72:73], -1.0 op_sel_hi:[1,0,0]
	v_pk_fma_f32 v[166:167], v[166:167], s[72:73], -1.0 op_sel_hi:[1,0,0]
	v_pk_fma_f32 v[172:173], v[172:173], s[72:73], -1.0 op_sel_hi:[1,0,0]
	v_pk_fma_f32 v[182:183], v[182:183], s[72:73], -1.0 op_sel_hi:[1,0,0]
	v_pk_fma_f32 v[162:163], v[160:161], s[74:75], v[198:199] op_sel_hi:[1,0,0]
	v_pk_fma_f32 v[168:169], v[166:167], s[74:75], v[198:199] op_sel_hi:[1,0,0]
	v_pk_fma_f32 v[178:179], v[172:173], s[74:75], v[198:199] op_sel_hi:[1,0,0]
	v_pk_fma_f32 v[184:185], v[182:183], s[74:75], v[198:199] op_sel_hi:[1,0,0]
	v_pk_fma_f32 v[162:163], v[160:161], v[162:163], s[2:3] op_sel_hi:[1,1,0]
	v_pk_fma_f32 v[168:169], v[166:167], v[168:169], s[2:3] op_sel_hi:[1,1,0]
	v_pk_fma_f32 v[178:179], v[172:173], v[178:179], s[2:3] op_sel_hi:[1,1,0]
	v_pk_fma_f32 v[184:185], v[182:183], v[184:185], s[2:3] op_sel_hi:[1,1,0]
	v_pk_fma_f32 v[162:163], v[160:161], v[162:163], s[28:29] op_sel_hi:[1,1,0]
	v_pk_fma_f32 v[168:169], v[166:167], v[168:169], s[28:29] op_sel_hi:[1,1,0]
	v_pk_fma_f32 v[178:179], v[172:173], v[178:179], s[28:29] op_sel_hi:[1,1,0]
	v_pk_fma_f32 v[184:185], v[182:183], v[184:185], s[28:29] op_sel_hi:[1,1,0]
	v_pk_fma_f32 v[162:163], v[160:161], v[162:163], s[30:31] op_sel_hi:[1,1,0]
	v_pk_fma_f32 v[168:169], v[166:167], v[168:169], s[30:31] op_sel_hi:[1,1,0]
	v_pk_fma_f32 v[178:179], v[172:173], v[178:179], s[30:31] op_sel_hi:[1,1,0]
	v_pk_fma_f32 v[184:185], v[182:183], v[184:185], s[30:31] op_sel_hi:[1,1,0]
	v_pk_fma_f32 v[162:163], v[160:161], v[162:163], s[48:49] op_sel_hi:[1,1,0]
	v_pk_fma_f32 v[168:169], v[166:167], v[168:169], s[48:49] op_sel_hi:[1,1,0]
	v_pk_fma_f32 v[178:179], v[172:173], v[178:179], s[48:49] op_sel_hi:[1,1,0]
	v_pk_fma_f32 v[184:185], v[182:183], v[184:185], s[48:49] op_sel_hi:[1,1,0]
	v_pk_fma_f32 v[162:163], v[160:161], v[162:163], s[50:51] op_sel_hi:[1,1,0]
	v_pk_fma_f32 v[168:169], v[166:167], v[168:169], s[50:51] op_sel_hi:[1,1,0]
	v_pk_fma_f32 v[178:179], v[172:173], v[178:179], s[50:51] op_sel_hi:[1,1,0]
	v_pk_fma_f32 v[184:185], v[182:183], v[184:185], s[50:51] op_sel_hi:[1,1,0]
	v_pk_fma_f32 v[162:163], v[160:161], v[162:163], s[52:53] op_sel_hi:[1,1,0]
	v_pk_fma_f32 v[168:169], v[166:167], v[168:169], s[52:53] op_sel_hi:[1,1,0]
	v_pk_fma_f32 v[178:179], v[172:173], v[178:179], s[52:53] op_sel_hi:[1,1,0]
	v_pk_fma_f32 v[184:185], v[182:183], v[184:185], s[52:53] op_sel_hi:[1,1,0]
	v_pk_fma_f32 v[160:161], v[160:161], v[162:163], s[54:55] op_sel_hi:[1,1,0]
	v_pk_fma_f32 v[166:167], v[166:167], v[168:169], s[54:55] op_sel_hi:[1,1,0]
	v_pk_fma_f32 v[172:173], v[172:173], v[178:179], s[54:55] op_sel_hi:[1,1,0]
	v_pk_fma_f32 v[182:183], v[182:183], v[184:185], s[54:55] op_sel_hi:[1,1,0]
	v_pk_fma_f32 v[158:159], v[158:159], v[160:161], 0.5 op_sel_hi:[1,1,0]
	v_pk_fma_f32 v[164:165], v[164:165], v[166:167], 0.5 op_sel_hi:[1,1,0]
	v_pk_fma_f32 v[170:171], v[170:171], v[172:173], 0.5 op_sel_hi:[1,1,0]
	v_pk_fma_f32 v[180:181], v[180:181], v[182:183], 0.5 op_sel_hi:[1,1,0]
	v_pk_mul_f32 v[12:13], v[12:13], v[158:159]
	v_pk_mul_f32 v[14:15], v[14:15], v[164:165]
	v_pk_mul_f32 v[4:5], v[4:5], v[170:171]
	v_pk_mul_f32 v[6:7], v[6:7], v[180:181]
	v_pk_add_f32 v[158:159], v[16:17], v[18:19]
	v_pk_add_f32 v[160:161], v[8:9], v[10:11]
	v_pk_add_f32 v[162:163], v[12:13], v[14:15]
	v_pk_add_f32 v[164:165], v[4:5], v[6:7]
	v_pk_mul_f32 v[166:167], v[16:17], v[16:17]
	v_pk_mul_f32 v[168:169], v[8:9], v[8:9]
	v_pk_mul_f32 v[170:171], v[12:13], v[12:13]
	v_pk_mul_f32 v[172:173], v[4:5], v[4:5]
	v_pk_fma_f32 v[166:167], v[18:19], v[18:19], v[166:167]
	v_pk_fma_f32 v[168:169], v[10:11], v[10:11], v[168:169]
	v_pk_fma_f32 v[170:171], v[14:15], v[14:15], v[170:171]
	v_pk_fma_f32 v[172:173], v[6:7], v[6:7], v[172:173]
	v_pk_add_f32 v[158:159], v[158:159], v[160:161]
	v_pk_add_f32 v[162:163], v[162:163], v[164:165]
	v_pk_add_f32 v[166:167], v[166:167], v[168:169]
	v_pk_add_f32 v[170:171], v[170:171], v[172:173]
	v_pk_add_f32 v[158:159], v[158:159], v[162:163]
	v_pk_add_f32 v[166:167], v[166:167], v[170:171]
	v_cvt_pk_bf16_f32 v16, v16, v17
	v_cvt_pk_bf16_f32 v17, v18, v19
	v_cvt_pk_bf16_f32 v18, v8, v9
	v_cvt_pk_bf16_f32 v19, v10, v11
	global_store_dwordx4 v215, v[16:19], s[12:13]
	v_cvt_pk_bf16_f32 v12, v12, v13
	v_cvt_pk_bf16_f32 v13, v14, v15
	v_cvt_pk_bf16_f32 v14, v4, v5
	v_cvt_pk_bf16_f32 v15, v6, v7
	global_store_dwordx4 v215, v[12:15], s[12:13] offset:256
	v_add_f32_e32 v8, v158, v159
	v_add_f32_e32 v9, v166, v167
	ds_bpermute_b32 v122, v146, v120
	ds_bpermute_b32 v123, v146, v121
	ds_bpermute_b32 v106, v146, v104
	ds_bpermute_b32 v107, v146, v105
	ds_bpermute_b32 v90, v146, v88
	ds_bpermute_b32 v91, v146, v89
	ds_bpermute_b32 v74, v146, v72
	ds_bpermute_b32 v75, v146, v73
	ds_bpermute_b32 v58, v146, v56
	ds_bpermute_b32 v59, v146, v57
	ds_bpermute_b32 v42, v146, v40
	ds_bpermute_b32 v43, v146, v41
	ds_bpermute_b32 v26, v146, v24
	ds_bpermute_b32 v27, v146, v25
	ds_bpermute_b32 v10, v146, v8
	ds_bpermute_b32 v11, v146, v9
	s_waitcnt lgkmcnt(0)
	v_pk_add_f32 v[120:121], v[120:121], v[122:123]
	v_pk_add_f32 v[104:105], v[104:105], v[106:107]
	v_pk_add_f32 v[88:89], v[88:89], v[90:91]
	v_pk_add_f32 v[72:73], v[72:73], v[74:75]
	v_pk_add_f32 v[56:57], v[56:57], v[58:59]
	v_pk_add_f32 v[40:41], v[40:41], v[42:43]
	v_pk_add_f32 v[24:25], v[24:25], v[26:27]
	v_pk_add_f32 v[8:9], v[8:9], v[10:11]
	ds_bpermute_b32 v122, v147, v120
	ds_bpermute_b32 v123, v147, v121
	ds_bpermute_b32 v106, v147, v104
	ds_bpermute_b32 v107, v147, v105
	ds_bpermute_b32 v90, v147, v88
	ds_bpermute_b32 v91, v147, v89
	ds_bpermute_b32 v74, v147, v72
	ds_bpermute_b32 v75, v147, v73
	ds_bpermute_b32 v58, v147, v56
	ds_bpermute_b32 v59, v147, v57
	ds_bpermute_b32 v42, v147, v40
	ds_bpermute_b32 v43, v147, v41
	ds_bpermute_b32 v26, v147, v24
	ds_bpermute_b32 v27, v147, v25
	ds_bpermute_b32 v10, v147, v8
	ds_bpermute_b32 v11, v147, v9
	s_waitcnt lgkmcnt(0)
	v_pk_add_f32 v[120:121], v[120:121], v[122:123]
	v_pk_add_f32 v[104:105], v[104:105], v[106:107]
	v_pk_add_f32 v[88:89], v[88:89], v[90:91]
	v_pk_add_f32 v[72:73], v[72:73], v[74:75]
	v_pk_add_f32 v[56:57], v[56:57], v[58:59]
	v_pk_add_f32 v[40:41], v[40:41], v[42:43]
	v_pk_add_f32 v[24:25], v[24:25], v[26:27]
	v_pk_add_f32 v[8:9], v[8:9], v[10:11]
	s_and_saveexec_b64 s[0:1], s[4:5]
	global_store_dwordx2 v216, v[120:121], s[14:15]
	global_store_dwordx2 v217, v[104:105], s[14:15]
	global_store_dwordx2 v218, v[88:89], s[14:15]
	global_store_dwordx2 v219, v[72:73], s[14:15]
	global_store_dwordx2 v220, v[56:57], s[14:15]
	global_store_dwordx2 v221, v[40:41], s[14:15]
	global_store_dwordx2 v186, v[24:25], s[14:15]
	global_store_dwordx2 v187, v[8:9], s[14:15]
